# multi-scale pooling task hand-written: prelude window loads batched under lane-group masks, 8-row groups' current + trailing loads requested one group ahead (no per-row conditional load + full wait)
# baseline (speedup 1.0000x reference)
; __device__ __forceinline__ float bf_lo(unsigned w) { return __uint_as_float(w << 16); }
; __device__ __forceinline__ float bf_hi(unsigned w) { return __uint_as_float(w & 0xffff0000u); }
; __global__ void __launch_bounds__(NWAVES * 64, 2) trunk_fwd(Args args) {
;     ...
;             { const int w = 2 << (lane >> 4);
;               for (int task = gw; task < M / 32; task += NGW) {
;                 const int row0 = task * 32, t0 = row0 & (SEQ - 1);
;                 const bf16* up = BIG + (size_t)row0 * 2048 + 1536 + lane * 8; bf16* op = MIX + (size_t)row0 * 1024 + 512 + lane * 8;
;                 float sum[8];
; #pragma unroll
;                 for (int e = 0; e < 8; ++e) sum[e] = 0.f;
;                 if (t0 > 0) for (int jj = 1; jj <= w; ++jj) {   const v4u q = *(const v4u*)(up - (size_t)jj * 2048);
;                     sum[0] += bf_lo(q.x); sum[1] += bf_hi(q.x); sum[2] += bf_lo(q.y); sum[3] += bf_hi(q.y); sum[4] += bf_lo(q.z); sum[5] += bf_hi(q.z); sum[6] += bf_lo(q.w); sum[7] += bf_hi(q.w); }
;                 for (int i0 = 0; i0 < 32; i0 += 4) {
;                     v4u qq[4], oo[4];
; #pragma unroll
;                     for (int k = 0; k < 4; ++k) { qq[k] = *(const v4u*)(up + (size_t)(i0 + k) * 2048); oo[k] = *(const v4u*)(up + ((long)(i0 + k) - w) * 2048); }
.LBB0_615:
	s_ashr_i32 s5, s4, 31
	s_lshl_b64 s[68:69], s[4:5], 12
	s_and_b32 s7, s48, 7
	s_lshl_b32 s7, s7, 25
	s_add_u32 s68, s68, s7
	s_addc_u32 s69, s69, 0
	s_and_b32 s14, s4, 0xfe0
	s_lshl_b64 s[6:7], s[4:5], 11
	s_add_u32 s6, s18, s6
	s_addc_u32 s7, s19, s7
	s_add_u32 s6, s6, 0x14a00400
	s_addc_u32 s7, s7, 0
	s_add_u32 s8, s18, s68
	s_addc_u32 s9, s19, s69
	s_add_u32 s8, s8, 0x1ca00c00
	s_addc_u32 s9, s9, 0
	v_mov_b32_e32 v60, v0
	v_mov_b32_e32 v61, 0
	v_lshl_add_u64 v[58:59], s[8:9], 0, v[60:61]
	v_lshlrev_b32_e32 v2, 12, v52
	v_mov_b32_e32 v3, 0
	v_sub_co_u32_e32 v62, vcc, v58, v2
	s_nop 1
	v_subb_co_u32_e32 v63, vcc, v59, v3, vcc
	v_lshl_add_u64 v[56:57], s[6:7], 0, v[60:61]
	v_mov_b32_e32 v32, 0
	v_mov_b32_e32 v33, 0
	v_mov_b32_e32 v34, 0
	v_mov_b32_e32 v35, 0
	v_mov_b32_e32 v36, 0
	v_mov_b32_e32 v37, 0
	v_mov_b32_e32 v38, 0
	v_mov_b32_e32 v39, 0
	s_cmp_eq_u32 s14, 0
	s_cbranch_scc1 .Lpool_nopre
	v_add_co_u32_e32 v4, vcc, 0xfffff000, v58
	s_nop 1
	v_addc_co_u32_e32 v5, vcc, -1, v59, vcc
	s_mov_b32 exec_lo, -1
	s_mov_b32 exec_hi, -1
	global_load_dwordx4 v[128:131], v[4:5], off
	global_load_dwordx4 v[132:135], v[4:5], off offset:-4096
	s_mov_b32 exec_lo, 0xffff0000
	s_mov_b32 exec_hi, -1
	v_add_co_u32_e32 v4, vcc, 0xffffe000, v4
	s_nop 1
	v_addc_co_u32_e32 v5, vcc, -1, v5, vcc
	global_load_dwordx4 v[136:139], v[4:5], off
	global_load_dwordx4 v[140:143], v[4:5], off offset:-4096
	s_mov_b32 exec_lo, 0
	s_mov_b32 exec_hi, -1
	v_add_co_u32_e32 v4, vcc, 0xffffe000, v4
	s_nop 1
	v_addc_co_u32_e32 v5, vcc, -1, v5, vcc
	global_load_dwordx4 v[144:147], v[4:5], off
	global_load_dwordx4 v[148:151], v[4:5], off offset:-4096
	v_add_co_u32_e32 v4, vcc, 0xffffe000, v4
	s_nop 1
	v_addc_co_u32_e32 v5, vcc, -1, v5, vcc
	global_load_dwordx4 v[152:155], v[4:5], off
	global_load_dwordx4 v[156:159], v[4:5], off offset:-4096
	s_mov_b32 exec_lo, 0
	s_mov_b32 exec_hi, 0xffff0000
	v_add_co_u32_e32 v4, vcc, 0xffffe000, v4
	s_nop 1
	v_addc_co_u32_e32 v5, vcc, -1, v5, vcc
	global_load_dwordx4 v[160:163], v[4:5], off
	global_load_dwordx4 v[164:167], v[4:5], off offset:-4096
	v_add_co_u32_e32 v4, vcc, 0xffffe000, v4
	s_nop 1
	v_addc_co_u32_e32 v5, vcc, -1, v5, vcc
	global_load_dwordx4 v[168:171], v[4:5], off
	global_load_dwordx4 v[172:175], v[4:5], off offset:-4096
	v_add_co_u32_e32 v4, vcc, 0xffffe000, v4
	s_nop 1
	v_addc_co_u32_e32 v5, vcc, -1, v5, vcc
	global_load_dwordx4 v[176:179], v[4:5], off
	global_load_dwordx4 v[180:183], v[4:5], off offset:-4096
	v_add_co_u32_e32 v4, vcc, 0xffffe000, v4
	s_nop 1
	v_addc_co_u32_e32 v5, vcc, -1, v5, vcc
	global_load_dwordx4 v[184:187], v[4:5], off
	global_load_dwordx4 v[188:191], v[4:5], off offset:-4096
	s_mov_b64 exec, -1
	v_add_co_u32_e32 v4, vcc, 0x1000, v58
	s_nop 1
	v_addc_co_u32_e32 v5, vcc, 0, v59, vcc
	v_add_co_u32_e32 v6, vcc, 0x1000, v62
	s_nop 1
	v_addc_co_u32_e32 v7, vcc, 0, v63, vcc
	global_load_dwordx4 v[64:67], v[4:5], off offset:-4096
	global_load_dwordx4 v[68:71], v[6:7], off offset:-4096
	global_load_dwordx4 v[72:75], v[4:5], off
	global_load_dwordx4 v[76:79], v[6:7], off
	v_add_co_u32_e32 v4, vcc, 0x3000, v58
	s_nop 1
	v_addc_co_u32_e32 v5, vcc, 0, v59, vcc
	v_add_co_u32_e32 v6, vcc, 0x3000, v62
	s_nop 1
	v_addc_co_u32_e32 v7, vcc, 0, v63, vcc
	global_load_dwordx4 v[80:83], v[4:5], off offset:-4096
	global_load_dwordx4 v[84:87], v[6:7], off offset:-4096
	global_load_dwordx4 v[88:91], v[4:5], off
	global_load_dwordx4 v[92:95], v[6:7], off
	v_add_co_u32_e32 v4, vcc, 0x5000, v58
	s_nop 1
	v_addc_co_u32_e32 v5, vcc, 0, v59, vcc
	v_add_co_u32_e32 v6, vcc, 0x5000, v62
	s_nop 1
	v_addc_co_u32_e32 v7, vcc, 0, v63, vcc
	global_load_dwordx4 v[96:99], v[4:5], off offset:-4096
	global_load_dwordx4 v[100:103], v[6:7], off offset:-4096
	global_load_dwordx4 v[104:107], v[4:5], off
	global_load_dwordx4 v[108:111], v[6:7], off
	v_add_co_u32_e32 v4, vcc, 0x7000, v58
	s_nop 1
	v_addc_co_u32_e32 v5, vcc, 0, v59, vcc
	v_add_co_u32_e32 v6, vcc, 0x7000, v62
	s_nop 1
	v_addc_co_u32_e32 v7, vcc, 0, v63, vcc
	global_load_dwordx4 v[112:115], v[4:5], off offset:-4096
	global_load_dwordx4 v[116:119], v[6:7], off offset:-4096
	global_load_dwordx4 v[120:123], v[4:5], off
	global_load_dwordx4 v[124:127], v[6:7], off
	s_waitcnt vmcnt(31)
	v_lshlrev_b32_e32 v8, 16, v128
	v_and_b32_e32 v9, 0xffff0000, v128
	v_lshlrev_b32_e32 v10, 16, v129
	v_and_b32_e32 v11, 0xffff0000, v129
	v_lshlrev_b32_e32 v12, 16, v130
	v_and_b32_e32 v13, 0xffff0000, v130
	v_lshlrev_b32_e32 v14, 16, v131
	v_and_b32_e32 v15, 0xffff0000, v131
	v_pk_add_f32 v[32:33], v[32:33], v[8:9]
	v_pk_add_f32 v[34:35], v[34:35], v[10:11]
	v_pk_add_f32 v[36:37], v[36:37], v[12:13]
	v_pk_add_f32 v[38:39], v[38:39], v[14:15]
	s_waitcnt vmcnt(30)
	v_lshlrev_b32_e32 v8, 16, v132
	v_and_b32_e32 v9, 0xffff0000, v132
	v_lshlrev_b32_e32 v10, 16, v133
	v_and_b32_e32 v11, 0xffff0000, v133
	v_lshlrev_b32_e32 v12, 16, v134
	v_and_b32_e32 v13, 0xffff0000, v134
	v_lshlrev_b32_e32 v14, 16, v135
	v_and_b32_e32 v15, 0xffff0000, v135
	v_pk_add_f32 v[32:33], v[32:33], v[8:9]
	v_pk_add_f32 v[34:35], v[34:35], v[10:11]
	v_pk_add_f32 v[36:37], v[36:37], v[12:13]
	v_pk_add_f32 v[38:39], v[38:39], v[14:15]
	s_mov_b32 exec_lo, 0xffff0000
	s_mov_b32 exec_hi, -1
	s_waitcnt vmcnt(29)
	v_lshlrev_b32_e32 v8, 16, v136
	v_and_b32_e32 v9, 0xffff0000, v136
	v_lshlrev_b32_e32 v10, 16, v137
	v_and_b32_e32 v11, 0xffff0000, v137
	v_lshlrev_b32_e32 v12, 16, v138
	v_and_b32_e32 v13, 0xffff0000, v138
	v_lshlrev_b32_e32 v14, 16, v139
	v_and_b32_e32 v15, 0xffff0000, v139
	v_pk_add_f32 v[32:33], v[32:33], v[8:9]
	v_pk_add_f32 v[34:35], v[34:35], v[10:11]
	v_pk_add_f32 v[36:37], v[36:37], v[12:13]
	v_pk_add_f32 v[38:39], v[38:39], v[14:15]
	s_waitcnt vmcnt(28)
; __device__ __forceinline__ float bf_lo(unsigned w) { return __uint_as_float(w << 16); }
; __device__ __forceinline__ float bf_hi(unsigned w) { return __uint_as_float(w & 0xffff0000u); }
; __global__ void __launch_bounds__(NWAVES * 64, 2) trunk_fwd(Args args) {
;     ...
;                 if (t0 > 0) for (int jj = 1; jj <= w; ++jj) {   const v4u q = *(const v4u*)(up - (size_t)jj * 2048);
;                     sum[0] += bf_lo(q.x); sum[1] += bf_hi(q.x); sum[2] += bf_lo(q.y); sum[3] += bf_hi(q.y); sum[4] += bf_lo(q.z); sum[5] += bf_hi(q.z); sum[6] += bf_lo(q.w); sum[7] += bf_hi(q.w); }
	v_lshlrev_b32_e32 v8, 16, v140
	v_and_b32_e32 v9, 0xffff0000, v140
	v_lshlrev_b32_e32 v10, 16, v141
	v_and_b32_e32 v11, 0xffff0000, v141
	v_lshlrev_b32_e32 v12, 16, v142
	v_and_b32_e32 v13, 0xffff0000, v142
	v_lshlrev_b32_e32 v14, 16, v143
	v_and_b32_e32 v15, 0xffff0000, v143
	v_pk_add_f32 v[32:33], v[32:33], v[8:9]
	v_pk_add_f32 v[34:35], v[34:35], v[10:11]
	v_pk_add_f32 v[36:37], v[36:37], v[12:13]
	v_pk_add_f32 v[38:39], v[38:39], v[14:15]
	s_mov_b32 exec_lo, 0
	s_mov_b32 exec_hi, -1
	s_waitcnt vmcnt(27)
	v_lshlrev_b32_e32 v8, 16, v144
	v_and_b32_e32 v9, 0xffff0000, v144
	v_lshlrev_b32_e32 v10, 16, v145
	v_and_b32_e32 v11, 0xffff0000, v145
	v_lshlrev_b32_e32 v12, 16, v146
	v_and_b32_e32 v13, 0xffff0000, v146
	v_lshlrev_b32_e32 v14, 16, v147
	v_and_b32_e32 v15, 0xffff0000, v147
	v_pk_add_f32 v[32:33], v[32:33], v[8:9]
	v_pk_add_f32 v[34:35], v[34:35], v[10:11]
	v_pk_add_f32 v[36:37], v[36:37], v[12:13]
	v_pk_add_f32 v[38:39], v[38:39], v[14:15]
	s_waitcnt vmcnt(26)
	v_lshlrev_b32_e32 v8, 16, v148
	v_and_b32_e32 v9, 0xffff0000, v148
	v_lshlrev_b32_e32 v10, 16, v149
	v_and_b32_e32 v11, 0xffff0000, v149
	v_lshlrev_b32_e32 v12, 16, v150
	v_and_b32_e32 v13, 0xffff0000, v150
	v_lshlrev_b32_e32 v14, 16, v151
	v_and_b32_e32 v15, 0xffff0000, v151
	v_pk_add_f32 v[32:33], v[32:33], v[8:9]
	v_pk_add_f32 v[34:35], v[34:35], v[10:11]
	v_pk_add_f32 v[36:37], v[36:37], v[12:13]
	v_pk_add_f32 v[38:39], v[38:39], v[14:15]
	s_waitcnt vmcnt(25)
	v_lshlrev_b32_e32 v8, 16, v152
	v_and_b32_e32 v9, 0xffff0000, v152
	v_lshlrev_b32_e32 v10, 16, v153
	v_and_b32_e32 v11, 0xffff0000, v153
	v_lshlrev_b32_e32 v12, 16, v154
	v_and_b32_e32 v13, 0xffff0000, v154
	v_lshlrev_b32_e32 v14, 16, v155
	v_and_b32_e32 v15, 0xffff0000, v155
	v_pk_add_f32 v[32:33], v[32:33], v[8:9]
	v_pk_add_f32 v[34:35], v[34:35], v[10:11]
	v_pk_add_f32 v[36:37], v[36:37], v[12:13]
	v_pk_add_f32 v[38:39], v[38:39], v[14:15]
	s_waitcnt vmcnt(24)
	v_lshlrev_b32_e32 v8, 16, v156
	v_and_b32_e32 v9, 0xffff0000, v156
	v_lshlrev_b32_e32 v10, 16, v157
	v_and_b32_e32 v11, 0xffff0000, v157
	v_lshlrev_b32_e32 v12, 16, v158
	v_and_b32_e32 v13, 0xffff0000, v158
	v_lshlrev_b32_e32 v14, 16, v159
	v_and_b32_e32 v15, 0xffff0000, v159
	v_pk_add_f32 v[32:33], v[32:33], v[8:9]
	v_pk_add_f32 v[34:35], v[34:35], v[10:11]
	v_pk_add_f32 v[36:37], v[36:37], v[12:13]
	v_pk_add_f32 v[38:39], v[38:39], v[14:15]
	s_mov_b32 exec_lo, 0
	s_mov_b32 exec_hi, 0xffff0000
	s_waitcnt vmcnt(23)
	v_lshlrev_b32_e32 v8, 16, v160
	v_and_b32_e32 v9, 0xffff0000, v160
	v_lshlrev_b32_e32 v10, 16, v161
	v_and_b32_e32 v11, 0xffff0000, v161
	v_lshlrev_b32_e32 v12, 16, v162
	v_and_b32_e32 v13, 0xffff0000, v162
	v_lshlrev_b32_e32 v14, 16, v163
	v_and_b32_e32 v15, 0xffff0000, v163
	v_pk_add_f32 v[32:33], v[32:33], v[8:9]
	v_pk_add_f32 v[34:35], v[34:35], v[10:11]
	v_pk_add_f32 v[36:37], v[36:37], v[12:13]
	v_pk_add_f32 v[38:39], v[38:39], v[14:15]
	s_waitcnt vmcnt(22)
	v_lshlrev_b32_e32 v8, 16, v164
	v_and_b32_e32 v9, 0xffff0000, v164
	v_lshlrev_b32_e32 v10, 16, v165
	v_and_b32_e32 v11, 0xffff0000, v165
	v_lshlrev_b32_e32 v12, 16, v166
	v_and_b32_e32 v13, 0xffff0000, v166
	v_lshlrev_b32_e32 v14, 16, v167
	v_and_b32_e32 v15, 0xffff0000, v167
	v_pk_add_f32 v[32:33], v[32:33], v[8:9]
	v_pk_add_f32 v[34:35], v[34:35], v[10:11]
	v_pk_add_f32 v[36:37], v[36:37], v[12:13]
	v_pk_add_f32 v[38:39], v[38:39], v[14:15]
	s_waitcnt vmcnt(21)
	v_lshlrev_b32_e32 v8, 16, v168
	v_and_b32_e32 v9, 0xffff0000, v168
	v_lshlrev_b32_e32 v10, 16, v169
	v_and_b32_e32 v11, 0xffff0000, v169
	v_lshlrev_b32_e32 v12, 16, v170
	v_and_b32_e32 v13, 0xffff0000, v170
	v_lshlrev_b32_e32 v14, 16, v171
	v_and_b32_e32 v15, 0xffff0000, v171
	v_pk_add_f32 v[32:33], v[32:33], v[8:9]
	v_pk_add_f32 v[34:35], v[34:35], v[10:11]
	v_pk_add_f32 v[36:37], v[36:37], v[12:13]
	v_pk_add_f32 v[38:39], v[38:39], v[14:15]
	s_waitcnt vmcnt(20)
	v_lshlrev_b32_e32 v8, 16, v172
	v_and_b32_e32 v9, 0xffff0000, v172
	v_lshlrev_b32_e32 v10, 16, v173
	v_and_b32_e32 v11, 0xffff0000, v173
	v_lshlrev_b32_e32 v12, 16, v174
	v_and_b32_e32 v13, 0xffff0000, v174
	v_lshlrev_b32_e32 v14, 16, v175
	v_and_b32_e32 v15, 0xffff0000, v175
	v_pk_add_f32 v[32:33], v[32:33], v[8:9]
	v_pk_add_f32 v[34:35], v[34:35], v[10:11]
	v_pk_add_f32 v[36:37], v[36:37], v[12:13]
	v_pk_add_f32 v[38:39], v[38:39], v[14:15]
	s_waitcnt vmcnt(19)
	v_lshlrev_b32_e32 v8, 16, v176
	v_and_b32_e32 v9, 0xffff0000, v176
	v_lshlrev_b32_e32 v10, 16, v177
	v_and_b32_e32 v11, 0xffff0000, v177
	v_lshlrev_b32_e32 v12, 16, v178
	v_and_b32_e32 v13, 0xffff0000, v178
	v_lshlrev_b32_e32 v14, 16, v179
	v_and_b32_e32 v15, 0xffff0000, v179
	v_pk_add_f32 v[32:33], v[32:33], v[8:9]
	v_pk_add_f32 v[34:35], v[34:35], v[10:11]
	v_pk_add_f32 v[36:37], v[36:37], v[12:13]
	v_pk_add_f32 v[38:39], v[38:39], v[14:15]
	s_waitcnt vmcnt(18)
	v_lshlrev_b32_e32 v8, 16, v180
	v_and_b32_e32 v9, 0xffff0000, v180
	v_lshlrev_b32_e32 v10, 16, v181
	v_and_b32_e32 v11, 0xffff0000, v181
	v_lshlrev_b32_e32 v12, 16, v182
	v_and_b32_e32 v13, 0xffff0000, v182
	v_lshlrev_b32_e32 v14, 16, v183
	v_and_b32_e32 v15, 0xffff0000, v183
	v_pk_add_f32 v[32:33], v[32:33], v[8:9]
	v_pk_add_f32 v[34:35], v[34:35], v[10:11]
	v_pk_add_f32 v[36:37], v[36:37], v[12:13]
	v_pk_add_f32 v[38:39], v[38:39], v[14:15]
	s_waitcnt vmcnt(17)
	v_lshlrev_b32_e32 v8, 16, v184
	v_and_b32_e32 v9, 0xffff0000, v184
	v_lshlrev_b32_e32 v10, 16, v185
	v_and_b32_e32 v11, 0xffff0000, v185
	v_lshlrev_b32_e32 v12, 16, v186
	v_and_b32_e32 v13, 0xffff0000, v186
	v_lshlrev_b32_e32 v14, 16, v187
	v_and_b32_e32 v15, 0xffff0000, v187
	v_pk_add_f32 v[32:33], v[32:33], v[8:9]
	v_pk_add_f32 v[34:35], v[34:35], v[10:11]
	v_pk_add_f32 v[36:37], v[36:37], v[12:13]
	v_pk_add_f32 v[38:39], v[38:39], v[14:15]
	s_waitcnt vmcnt(16)
	v_lshlrev_b32_e32 v8, 16, v188
	v_and_b32_e32 v9, 0xffff0000, v188
	v_lshlrev_b32_e32 v10, 16, v189
	v_and_b32_e32 v11, 0xffff0000, v189
	v_lshlrev_b32_e32 v12, 16, v190
	v_and_b32_e32 v13, 0xffff0000, v190
	v_lshlrev_b32_e32 v14, 16, v191
	v_and_b32_e32 v15, 0xffff0000, v191
	v_pk_add_f32 v[32:33], v[32:33], v[8:9]
	v_pk_add_f32 v[34:35], v[34:35], v[10:11]
	v_pk_add_f32 v[36:37], v[36:37], v[12:13]
	v_pk_add_f32 v[38:39], v[38:39], v[14:15]
	s_mov_b64 exec, -1
	s_branch .Lpool_main
; __device__ __forceinline__ float bf_lo(unsigned w) { return __uint_as_float(w << 16); }
; __device__ __forceinline__ float bf_hi(unsigned w) { return __uint_as_float(w & 0xffff0000u); }
; __device__ __forceinline__ unsigned pk2(float lo, float hi) { return pg8::cvt_pk_bf16(lo, hi); }
; __global__ void __launch_bounds__(NWAVES * 64, 2) trunk_fwd(Args args) {
;     ...
;                 for (int i0 = 0; i0 < 32; i0 += 4) {
;                     v4u qq[4], oo[4];
; #pragma unroll
;                     for (int k = 0; k < 4; ++k) { qq[k] = *(const v4u*)(up + (size_t)(i0 + k) * 2048); oo[k] = *(const v4u*)(up + ((long)(i0 + k) - w) * 2048); }
; #pragma unroll
;                     for (int k = 0; k < 4; ++k) { const int i = i0 + k; const v4u q = qq[k], o = oo[k];
;                     float cur[8] = {bf_lo(q.x), bf_hi(q.x), bf_lo(q.y), bf_hi(q.y), bf_lo(q.z), bf_hi(q.z), bf_lo(q.w), bf_hi(q.w)};
; #pragma unroll
;                     for (int e = 0; e < 8; ++e) sum[e] += cur[e];
;                     const int t = t0 + i;
;                     if (t - w >= 0) {
;                         sum[0] -= bf_lo(o.x); sum[1] -= bf_hi(o.x); sum[2] -= bf_lo(o.y); sum[3] -= bf_hi(o.y); sum[4] -= bf_lo(o.z); sum[5] -= bf_hi(o.z); sum[6] -= bf_lo(o.w); sum[7] -= bf_hi(o.w); }
;                     const float rc = 1.0f / (float)((t + 1) < w ? (t + 1) : w);
;                     v4u r; r.x = pk2(sum[0] * rc - cur[0], sum[1] * rc - cur[1]); r.y = pk2(sum[2] * rc - cur[2], sum[3] * rc - cur[3]); r.z = pk2(sum[4] * rc - cur[4], sum[5] * rc - cur[5]); r.w = pk2(sum[6] * rc - cur[6], sum[7] * rc - cur[7]);
;                     *(v4u*)(op + (size_t)i * 1024) = r; }
.Lpool_nopre:
	v_add_co_u32_e32 v4, vcc, 0x1000, v58
	s_nop 1
	v_addc_co_u32_e32 v5, vcc, 0, v59, vcc
	v_add_co_u32_e32 v6, vcc, 0x1000, v62
	s_nop 1
	v_addc_co_u32_e32 v7, vcc, 0, v63, vcc
	global_load_dwordx4 v[64:67], v[4:5], off offset:-4096
	global_load_dwordx4 v[68:71], v[6:7], off offset:-4096
	global_load_dwordx4 v[72:75], v[4:5], off
	global_load_dwordx4 v[76:79], v[6:7], off
	v_add_co_u32_e32 v4, vcc, 0x3000, v58
	s_nop 1
	v_addc_co_u32_e32 v5, vcc, 0, v59, vcc
	v_add_co_u32_e32 v6, vcc, 0x3000, v62
	s_nop 1
	v_addc_co_u32_e32 v7, vcc, 0, v63, vcc
	global_load_dwordx4 v[80:83], v[4:5], off offset:-4096
	global_load_dwordx4 v[84:87], v[6:7], off offset:-4096
	global_load_dwordx4 v[88:91], v[4:5], off
	global_load_dwordx4 v[92:95], v[6:7], off
	v_add_co_u32_e32 v4, vcc, 0x5000, v58
	s_nop 1
	v_addc_co_u32_e32 v5, vcc, 0, v59, vcc
	v_add_co_u32_e32 v6, vcc, 0x5000, v62
	s_nop 1
	v_addc_co_u32_e32 v7, vcc, 0, v63, vcc
	global_load_dwordx4 v[96:99], v[4:5], off offset:-4096
	global_load_dwordx4 v[100:103], v[6:7], off offset:-4096
	global_load_dwordx4 v[104:107], v[4:5], off
	global_load_dwordx4 v[108:111], v[6:7], off
	v_add_co_u32_e32 v4, vcc, 0x7000, v58
	s_nop 1
	v_addc_co_u32_e32 v5, vcc, 0, v59, vcc
	v_add_co_u32_e32 v6, vcc, 0x7000, v62
	s_nop 1
	v_addc_co_u32_e32 v7, vcc, 0, v63, vcc
	global_load_dwordx4 v[112:115], v[4:5], off offset:-4096
	global_load_dwordx4 v[116:119], v[6:7], off offset:-4096
	global_load_dwordx4 v[120:123], v[4:5], off
	global_load_dwordx4 v[124:127], v[6:7], off
.Lpool_main:
	v_add_co_u32_e32 v4, vcc, 0x9000, v58
	s_nop 1
	v_addc_co_u32_e32 v5, vcc, 0, v59, vcc
	v_add_co_u32_e32 v6, vcc, 0x9000, v62
	s_nop 1
	v_addc_co_u32_e32 v7, vcc, 0, v63, vcc
	global_load_dwordx4 v[128:131], v[4:5], off offset:-4096
	global_load_dwordx4 v[132:135], v[6:7], off offset:-4096
	global_load_dwordx4 v[136:139], v[4:5], off
	global_load_dwordx4 v[140:143], v[6:7], off
	v_add_co_u32_e32 v4, vcc, 0xb000, v58
	s_nop 1
	v_addc_co_u32_e32 v5, vcc, 0, v59, vcc
	v_add_co_u32_e32 v6, vcc, 0xb000, v62
	s_nop 1
	v_addc_co_u32_e32 v7, vcc, 0, v63, vcc
	global_load_dwordx4 v[144:147], v[4:5], off offset:-4096
	global_load_dwordx4 v[148:151], v[6:7], off offset:-4096
	global_load_dwordx4 v[152:155], v[4:5], off
	global_load_dwordx4 v[156:159], v[6:7], off
	v_add_co_u32_e32 v4, vcc, 0xd000, v58
	s_nop 1
	v_addc_co_u32_e32 v5, vcc, 0, v59, vcc
	v_add_co_u32_e32 v6, vcc, 0xd000, v62
	s_nop 1
	v_addc_co_u32_e32 v7, vcc, 0, v63, vcc
	global_load_dwordx4 v[160:163], v[4:5], off offset:-4096
	global_load_dwordx4 v[164:167], v[6:7], off offset:-4096
	global_load_dwordx4 v[168:171], v[4:5], off
	global_load_dwordx4 v[172:175], v[6:7], off
	v_add_co_u32_e32 v4, vcc, 0xf000, v58
	s_nop 1
	v_addc_co_u32_e32 v5, vcc, 0, v59, vcc
	v_add_co_u32_e32 v6, vcc, 0xf000, v62
	s_nop 1
	v_addc_co_u32_e32 v7, vcc, 0, v63, vcc
	global_load_dwordx4 v[176:179], v[4:5], off offset:-4096
	global_load_dwordx4 v[180:183], v[6:7], off offset:-4096
	global_load_dwordx4 v[184:187], v[4:5], off
	global_load_dwordx4 v[188:191], v[6:7], off
	s_waitcnt vmcnt(30)
	v_lshlrev_b32_e32 v8, 16, v64
	v_and_b32_e32 v9, 0xffff0000, v64
	v_lshlrev_b32_e32 v10, 16, v65
	v_and_b32_e32 v11, 0xffff0000, v65
	v_lshlrev_b32_e32 v12, 16, v66
	v_and_b32_e32 v13, 0xffff0000, v66
	v_lshlrev_b32_e32 v14, 16, v67
	v_and_b32_e32 v15, 0xffff0000, v67
	v_pk_add_f32 v[32:33], v[32:33], v[8:9]
	v_pk_add_f32 v[34:35], v[34:35], v[10:11]
	v_pk_add_f32 v[36:37], v[36:37], v[12:13]
	v_pk_add_f32 v[38:39], v[38:39], v[14:15]
	s_add_i32 s20, s14, 0
	s_add_i32 s15, s20, 1
	v_cmp_ge_u32_e32 vcc, s20, v52
	v_lshlrev_b32_e32 v16, 16, v68
	v_and_b32_e32 v17, 0xffff0000, v68
	v_lshlrev_b32_e32 v18, 16, v69
	v_and_b32_e32 v19, 0xffff0000, v69
	v_lshlrev_b32_e32 v20, 16, v70
	v_and_b32_e32 v21, 0xffff0000, v70
	v_lshlrev_b32_e32 v22, 16, v71
	v_and_b32_e32 v23, 0xffff0000, v71
	s_and_saveexec_b64 s[26:27], vcc
	v_pk_add_f32 v[32:33], v[32:33], v[16:17] neg_lo:[0,1] neg_hi:[0,1]
	v_pk_add_f32 v[34:35], v[34:35], v[18:19] neg_lo:[0,1] neg_hi:[0,1]
	v_pk_add_f32 v[36:37], v[36:37], v[20:21] neg_lo:[0,1] neg_hi:[0,1]
	v_pk_add_f32 v[38:39], v[38:39], v[22:23] neg_lo:[0,1] neg_hi:[0,1]
	s_or_b64 exec, exec, s[26:27]
	v_min_u32_e32 v40, s15, v52
	v_cvt_f32_ubyte0_e32 v40, v40
	v_div_scale_f32 v41, s[26:27], v40, v40, 1.0
	v_rcp_f32_e32 v42, v41
	v_div_scale_f32 v43, vcc, 1.0, v40, 1.0
	v_fma_f32 v44, -v41, v42, 1.0
	v_fmac_f32_e32 v42, v44, v42
	v_mul_f32_e32 v44, v43, v42
	v_fma_f32 v45, -v41, v44, v43
	v_fmac_f32_e32 v44, v45, v42
	v_fma_f32 v41, -v41, v44, v43
	v_div_fmas_f32 v41, v41, v42, v44
	v_div_fixup_f32 v40, v41, v40, 1.0
	v_fma_f32 v46, v40, v32, -v8
	v_fma_f32 v47, v40, v33, -v9
	v_cvt_pk_bf16_f32 v24, v46, v47
	v_fma_f32 v46, v40, v34, -v10
	v_fma_f32 v47, v40, v35, -v11
	v_cvt_pk_bf16_f32 v25, v46, v47
	v_fma_f32 v46, v40, v36, -v12
	v_fma_f32 v47, v40, v37, -v13
	v_cvt_pk_bf16_f32 v26, v46, v47
	v_fma_f32 v46, v40, v38, -v14
	v_fma_f32 v47, v40, v39, -v15
	v_cvt_pk_bf16_f32 v27, v46, v47
	v_mov_b32_e32 v28, v56
	v_mov_b32_e32 v29, v57
	global_store_dwordx4 v[28:29], v[24:27], off
	s_waitcnt vmcnt(29)
; __device__ __forceinline__ float bf_lo(unsigned w) { return __uint_as_float(w << 16); }
; __device__ __forceinline__ float bf_hi(unsigned w) { return __uint_as_float(w & 0xffff0000u); }
; __device__ __forceinline__ unsigned pk2(float lo, float hi) { return pg8::cvt_pk_bf16(lo, hi); }
; __global__ void __launch_bounds__(NWAVES * 64, 2) trunk_fwd(Args args) {
;     ...
;                 for (int i0 = 0; i0 < 32; i0 += 4) {
;                     v4u qq[4], oo[4];
; #pragma unroll
;                     for (int k = 0; k < 4; ++k) { qq[k] = *(const v4u*)(up + (size_t)(i0 + k) * 2048); oo[k] = *(const v4u*)(up + ((long)(i0 + k) - w) * 2048); }
; #pragma unroll
;                     for (int k = 0; k < 4; ++k) { const int i = i0 + k; const v4u q = qq[k], o = oo[k];
;                     float cur[8] = {bf_lo(q.x), bf_hi(q.x), bf_lo(q.y), bf_hi(q.y), bf_lo(q.z), bf_hi(q.z), bf_lo(q.w), bf_hi(q.w)};
; #pragma unroll
;                     for (int e = 0; e < 8; ++e) sum[e] += cur[e];
;                     const int t = t0 + i;
;                     if (t - w >= 0) {
;                         sum[0] -= bf_lo(o.x); sum[1] -= bf_hi(o.x); sum[2] -= bf_lo(o.y); sum[3] -= bf_hi(o.y); sum[4] -= bf_lo(o.z); sum[5] -= bf_hi(o.z); sum[6] -= bf_lo(o.w); sum[7] -= bf_hi(o.w); }
;                     const float rc = 1.0f / (float)((t + 1) < w ? (t + 1) : w);
;                     v4u r; r.x = pk2(sum[0] * rc - cur[0], sum[1] * rc - cur[1]); r.y = pk2(sum[2] * rc - cur[2], sum[3] * rc - cur[3]); r.z = pk2(sum[4] * rc - cur[4], sum[5] * rc - cur[5]); r.w = pk2(sum[6] * rc - cur[6], sum[7] * rc - cur[7]);
;                     *(v4u*)(op + (size_t)i * 1024) = r; }
	v_lshlrev_b32_e32 v8, 16, v72
	v_and_b32_e32 v9, 0xffff0000, v72
	v_lshlrev_b32_e32 v10, 16, v73
	v_and_b32_e32 v11, 0xffff0000, v73
	v_lshlrev_b32_e32 v12, 16, v74
	v_and_b32_e32 v13, 0xffff0000, v74
	v_lshlrev_b32_e32 v14, 16, v75
	v_and_b32_e32 v15, 0xffff0000, v75
	v_pk_add_f32 v[32:33], v[32:33], v[8:9]
	v_pk_add_f32 v[34:35], v[34:35], v[10:11]
	v_pk_add_f32 v[36:37], v[36:37], v[12:13]
	v_pk_add_f32 v[38:39], v[38:39], v[14:15]
	s_add_i32 s20, s14, 1
	s_add_i32 s15, s20, 1
	v_cmp_ge_u32_e32 vcc, s20, v52
	v_lshlrev_b32_e32 v16, 16, v76
	v_and_b32_e32 v17, 0xffff0000, v76
	v_lshlrev_b32_e32 v18, 16, v77
	v_and_b32_e32 v19, 0xffff0000, v77
	v_lshlrev_b32_e32 v20, 16, v78
	v_and_b32_e32 v21, 0xffff0000, v78
	v_lshlrev_b32_e32 v22, 16, v79
	v_and_b32_e32 v23, 0xffff0000, v79
	s_and_saveexec_b64 s[26:27], vcc
	v_pk_add_f32 v[32:33], v[32:33], v[16:17] neg_lo:[0,1] neg_hi:[0,1]
	v_pk_add_f32 v[34:35], v[34:35], v[18:19] neg_lo:[0,1] neg_hi:[0,1]
	v_pk_add_f32 v[36:37], v[36:37], v[20:21] neg_lo:[0,1] neg_hi:[0,1]
	v_pk_add_f32 v[38:39], v[38:39], v[22:23] neg_lo:[0,1] neg_hi:[0,1]
	s_or_b64 exec, exec, s[26:27]
	v_min_u32_e32 v40, s15, v52
	v_cvt_f32_ubyte0_e32 v40, v40
	v_div_scale_f32 v41, s[26:27], v40, v40, 1.0
	v_rcp_f32_e32 v42, v41
	v_div_scale_f32 v43, vcc, 1.0, v40, 1.0
	v_fma_f32 v44, -v41, v42, 1.0
	v_fmac_f32_e32 v42, v44, v42
	v_mul_f32_e32 v44, v43, v42
	v_fma_f32 v45, -v41, v44, v43
	v_fmac_f32_e32 v44, v45, v42
	v_fma_f32 v41, -v41, v44, v43
	v_div_fmas_f32 v41, v41, v42, v44
	v_div_fixup_f32 v40, v41, v40, 1.0
	v_fma_f32 v46, v40, v32, -v8
	v_fma_f32 v47, v40, v33, -v9
	v_cvt_pk_bf16_f32 v24, v46, v47
	v_fma_f32 v46, v40, v34, -v10
	v_fma_f32 v47, v40, v35, -v11
	v_cvt_pk_bf16_f32 v25, v46, v47
	v_fma_f32 v46, v40, v36, -v12
	v_fma_f32 v47, v40, v37, -v13
	v_cvt_pk_bf16_f32 v26, v46, v47
	v_fma_f32 v46, v40, v38, -v14
	v_fma_f32 v47, v40, v39, -v15
	v_cvt_pk_bf16_f32 v27, v46, v47
	global_store_dwordx4 v[28:29], v[24:27], off offset:2048
	s_nop 1
	s_waitcnt vmcnt(28)
	v_lshlrev_b32_e32 v8, 16, v80
	v_and_b32_e32 v9, 0xffff0000, v80
	v_lshlrev_b32_e32 v10, 16, v81
	v_and_b32_e32 v11, 0xffff0000, v81
	v_lshlrev_b32_e32 v12, 16, v82
	v_and_b32_e32 v13, 0xffff0000, v82
	v_lshlrev_b32_e32 v14, 16, v83
	v_and_b32_e32 v15, 0xffff0000, v83
	v_pk_add_f32 v[32:33], v[32:33], v[8:9]
	v_pk_add_f32 v[34:35], v[34:35], v[10:11]
	v_pk_add_f32 v[36:37], v[36:37], v[12:13]
	v_pk_add_f32 v[38:39], v[38:39], v[14:15]
	s_add_i32 s20, s14, 2
	s_add_i32 s15, s20, 1
	v_cmp_ge_u32_e32 vcc, s20, v52
	v_lshlrev_b32_e32 v16, 16, v84
	v_and_b32_e32 v17, 0xffff0000, v84
	v_lshlrev_b32_e32 v18, 16, v85
	v_and_b32_e32 v19, 0xffff0000, v85
	v_lshlrev_b32_e32 v20, 16, v86
	v_and_b32_e32 v21, 0xffff0000, v86
	v_lshlrev_b32_e32 v22, 16, v87
	v_and_b32_e32 v23, 0xffff0000, v87
	s_and_saveexec_b64 s[26:27], vcc
	v_pk_add_f32 v[32:33], v[32:33], v[16:17] neg_lo:[0,1] neg_hi:[0,1]
	v_pk_add_f32 v[34:35], v[34:35], v[18:19] neg_lo:[0,1] neg_hi:[0,1]
	v_pk_add_f32 v[36:37], v[36:37], v[20:21] neg_lo:[0,1] neg_hi:[0,1]
	v_pk_add_f32 v[38:39], v[38:39], v[22:23] neg_lo:[0,1] neg_hi:[0,1]
	s_or_b64 exec, exec, s[26:27]
	v_min_u32_e32 v40, s15, v52
	v_cvt_f32_ubyte0_e32 v40, v40
	v_div_scale_f32 v41, s[26:27], v40, v40, 1.0
	v_rcp_f32_e32 v42, v41
	v_div_scale_f32 v43, vcc, 1.0, v40, 1.0
	v_fma_f32 v44, -v41, v42, 1.0
	v_fmac_f32_e32 v42, v44, v42
	v_mul_f32_e32 v44, v43, v42
	v_fma_f32 v45, -v41, v44, v43
	v_fmac_f32_e32 v44, v45, v42
	v_fma_f32 v41, -v41, v44, v43
	v_div_fmas_f32 v41, v41, v42, v44
	v_div_fixup_f32 v40, v41, v40, 1.0
	v_fma_f32 v46, v40, v32, -v8
	v_fma_f32 v47, v40, v33, -v9
	v_cvt_pk_bf16_f32 v24, v46, v47
	v_fma_f32 v46, v40, v34, -v10
	v_fma_f32 v47, v40, v35, -v11
	v_cvt_pk_bf16_f32 v25, v46, v47
	v_fma_f32 v46, v40, v36, -v12
	v_fma_f32 v47, v40, v37, -v13
	v_cvt_pk_bf16_f32 v26, v46, v47
	v_fma_f32 v46, v40, v38, -v14
	v_fma_f32 v47, v40, v39, -v15
	v_cvt_pk_bf16_f32 v27, v46, v47
	v_add_co_u32_e32 v28, vcc, 0x1000, v56
	s_nop 1
	v_addc_co_u32_e32 v29, vcc, 0, v57, vcc
	global_store_dwordx4 v[28:29], v[24:27], off
	s_waitcnt vmcnt(27)
	v_lshlrev_b32_e32 v8, 16, v88
	v_and_b32_e32 v9, 0xffff0000, v88
	v_lshlrev_b32_e32 v10, 16, v89
	v_and_b32_e32 v11, 0xffff0000, v89
	v_lshlrev_b32_e32 v12, 16, v90
	v_and_b32_e32 v13, 0xffff0000, v90
	v_lshlrev_b32_e32 v14, 16, v91
	v_and_b32_e32 v15, 0xffff0000, v91
	v_pk_add_f32 v[32:33], v[32:33], v[8:9]
	v_pk_add_f32 v[34:35], v[34:35], v[10:11]
	v_pk_add_f32 v[36:37], v[36:37], v[12:13]
	v_pk_add_f32 v[38:39], v[38:39], v[14:15]
	s_add_i32 s20, s14, 3
	s_add_i32 s15, s20, 1
	v_cmp_ge_u32_e32 vcc, s20, v52
	v_lshlrev_b32_e32 v16, 16, v92
	v_and_b32_e32 v17, 0xffff0000, v92
	v_lshlrev_b32_e32 v18, 16, v93
	v_and_b32_e32 v19, 0xffff0000, v93
	v_lshlrev_b32_e32 v20, 16, v94
	v_and_b32_e32 v21, 0xffff0000, v94
	v_lshlrev_b32_e32 v22, 16, v95
	v_and_b32_e32 v23, 0xffff0000, v95
	s_and_saveexec_b64 s[26:27], vcc
	v_pk_add_f32 v[32:33], v[32:33], v[16:17] neg_lo:[0,1] neg_hi:[0,1]
	v_pk_add_f32 v[34:35], v[34:35], v[18:19] neg_lo:[0,1] neg_hi:[0,1]
	v_pk_add_f32 v[36:37], v[36:37], v[20:21] neg_lo:[0,1] neg_hi:[0,1]
	v_pk_add_f32 v[38:39], v[38:39], v[22:23] neg_lo:[0,1] neg_hi:[0,1]
	s_or_b64 exec, exec, s[26:27]
	v_min_u32_e32 v40, s15, v52
	v_cvt_f32_ubyte0_e32 v40, v40
	v_div_scale_f32 v41, s[26:27], v40, v40, 1.0
	v_rcp_f32_e32 v42, v41
	v_div_scale_f32 v43, vcc, 1.0, v40, 1.0
	v_fma_f32 v44, -v41, v42, 1.0
	v_fmac_f32_e32 v42, v44, v42
	v_mul_f32_e32 v44, v43, v42
	v_fma_f32 v45, -v41, v44, v43
	v_fmac_f32_e32 v44, v45, v42
	v_fma_f32 v41, -v41, v44, v43
	v_div_fmas_f32 v41, v41, v42, v44
	v_div_fixup_f32 v40, v41, v40, 1.0
	v_fma_f32 v46, v40, v32, -v8
	v_fma_f32 v47, v40, v33, -v9
	v_cvt_pk_bf16_f32 v24, v46, v47
	v_fma_f32 v46, v40, v34, -v10
	v_fma_f32 v47, v40, v35, -v11
	v_cvt_pk_bf16_f32 v25, v46, v47
	v_fma_f32 v46, v40, v36, -v12
	v_fma_f32 v47, v40, v37, -v13
	v_cvt_pk_bf16_f32 v26, v46, v47
	v_fma_f32 v46, v40, v38, -v14
	v_fma_f32 v47, v40, v39, -v15
	v_cvt_pk_bf16_f32 v27, v46, v47
	global_store_dwordx4 v[28:29], v[24:27], off offset:2048
	s_nop 1
	s_waitcnt vmcnt(26)
; __device__ __forceinline__ float bf_lo(unsigned w) { return __uint_as_float(w << 16); }
; __device__ __forceinline__ float bf_hi(unsigned w) { return __uint_as_float(w & 0xffff0000u); }
; __device__ __forceinline__ unsigned pk2(float lo, float hi) { return pg8::cvt_pk_bf16(lo, hi); }
; __global__ void __launch_bounds__(NWAVES * 64, 2) trunk_fwd(Args args) {
;     ...
;                 for (int i0 = 0; i0 < 32; i0 += 4) {
;                     v4u qq[4], oo[4];
; #pragma unroll
;                     for (int k = 0; k < 4; ++k) { qq[k] = *(const v4u*)(up + (size_t)(i0 + k) * 2048); oo[k] = *(const v4u*)(up + ((long)(i0 + k) - w) * 2048); }
; #pragma unroll
;                     for (int k = 0; k < 4; ++k) { const int i = i0 + k; const v4u q = qq[k], o = oo[k];
;                     float cur[8] = {bf_lo(q.x), bf_hi(q.x), bf_lo(q.y), bf_hi(q.y), bf_lo(q.z), bf_hi(q.z), bf_lo(q.w), bf_hi(q.w)};
; #pragma unroll
;                     for (int e = 0; e < 8; ++e) sum[e] += cur[e];
;                     const int t = t0 + i;
;                     if (t - w >= 0) {
;                         sum[0] -= bf_lo(o.x); sum[1] -= bf_hi(o.x); sum[2] -= bf_lo(o.y); sum[3] -= bf_hi(o.y); sum[4] -= bf_lo(o.z); sum[5] -= bf_hi(o.z); sum[6] -= bf_lo(o.w); sum[7] -= bf_hi(o.w); }
;                     const float rc = 1.0f / (float)((t + 1) < w ? (t + 1) : w);
;                     v4u r; r.x = pk2(sum[0] * rc - cur[0], sum[1] * rc - cur[1]); r.y = pk2(sum[2] * rc - cur[2], sum[3] * rc - cur[3]); r.z = pk2(sum[4] * rc - cur[4], sum[5] * rc - cur[5]); r.w = pk2(sum[6] * rc - cur[6], sum[7] * rc - cur[7]);
;                     *(v4u*)(op + (size_t)i * 1024) = r; }
	v_lshlrev_b32_e32 v8, 16, v96
	v_and_b32_e32 v9, 0xffff0000, v96
	v_lshlrev_b32_e32 v10, 16, v97
	v_and_b32_e32 v11, 0xffff0000, v97
	v_lshlrev_b32_e32 v12, 16, v98
	v_and_b32_e32 v13, 0xffff0000, v98
	v_lshlrev_b32_e32 v14, 16, v99
	v_and_b32_e32 v15, 0xffff0000, v99
	v_pk_add_f32 v[32:33], v[32:33], v[8:9]
	v_pk_add_f32 v[34:35], v[34:35], v[10:11]
	v_pk_add_f32 v[36:37], v[36:37], v[12:13]
	v_pk_add_f32 v[38:39], v[38:39], v[14:15]
	s_add_i32 s20, s14, 4
	s_add_i32 s15, s20, 1
	v_cmp_ge_u32_e32 vcc, s20, v52
	v_lshlrev_b32_e32 v16, 16, v100
	v_and_b32_e32 v17, 0xffff0000, v100
	v_lshlrev_b32_e32 v18, 16, v101
	v_and_b32_e32 v19, 0xffff0000, v101
	v_lshlrev_b32_e32 v20, 16, v102
	v_and_b32_e32 v21, 0xffff0000, v102
	v_lshlrev_b32_e32 v22, 16, v103
	v_and_b32_e32 v23, 0xffff0000, v103
	s_and_saveexec_b64 s[26:27], vcc
	v_pk_add_f32 v[32:33], v[32:33], v[16:17] neg_lo:[0,1] neg_hi:[0,1]
	v_pk_add_f32 v[34:35], v[34:35], v[18:19] neg_lo:[0,1] neg_hi:[0,1]
	v_pk_add_f32 v[36:37], v[36:37], v[20:21] neg_lo:[0,1] neg_hi:[0,1]
	v_pk_add_f32 v[38:39], v[38:39], v[22:23] neg_lo:[0,1] neg_hi:[0,1]
	s_or_b64 exec, exec, s[26:27]
	v_min_u32_e32 v40, s15, v52
	v_cvt_f32_ubyte0_e32 v40, v40
	v_div_scale_f32 v41, s[26:27], v40, v40, 1.0
	v_rcp_f32_e32 v42, v41
	v_div_scale_f32 v43, vcc, 1.0, v40, 1.0
	v_fma_f32 v44, -v41, v42, 1.0
	v_fmac_f32_e32 v42, v44, v42
	v_mul_f32_e32 v44, v43, v42
	v_fma_f32 v45, -v41, v44, v43
	v_fmac_f32_e32 v44, v45, v42
	v_fma_f32 v41, -v41, v44, v43
	v_div_fmas_f32 v41, v41, v42, v44
	v_div_fixup_f32 v40, v41, v40, 1.0
	v_fma_f32 v46, v40, v32, -v8
	v_fma_f32 v47, v40, v33, -v9
	v_cvt_pk_bf16_f32 v24, v46, v47
	v_fma_f32 v46, v40, v34, -v10
	v_fma_f32 v47, v40, v35, -v11
	v_cvt_pk_bf16_f32 v25, v46, v47
	v_fma_f32 v46, v40, v36, -v12
	v_fma_f32 v47, v40, v37, -v13
	v_cvt_pk_bf16_f32 v26, v46, v47
	v_fma_f32 v46, v40, v38, -v14
	v_fma_f32 v47, v40, v39, -v15
	v_cvt_pk_bf16_f32 v27, v46, v47
	v_add_co_u32_e32 v28, vcc, 0x2000, v56
	s_nop 1
	v_addc_co_u32_e32 v29, vcc, 0, v57, vcc
	global_store_dwordx4 v[28:29], v[24:27], off
	s_waitcnt vmcnt(25)
	v_lshlrev_b32_e32 v8, 16, v104
	v_and_b32_e32 v9, 0xffff0000, v104
	v_lshlrev_b32_e32 v10, 16, v105
	v_and_b32_e32 v11, 0xffff0000, v105
	v_lshlrev_b32_e32 v12, 16, v106
	v_and_b32_e32 v13, 0xffff0000, v106
	v_lshlrev_b32_e32 v14, 16, v107
	v_and_b32_e32 v15, 0xffff0000, v107
	v_pk_add_f32 v[32:33], v[32:33], v[8:9]
	v_pk_add_f32 v[34:35], v[34:35], v[10:11]
	v_pk_add_f32 v[36:37], v[36:37], v[12:13]
	v_pk_add_f32 v[38:39], v[38:39], v[14:15]
	s_add_i32 s20, s14, 5
	s_add_i32 s15, s20, 1
	v_cmp_ge_u32_e32 vcc, s20, v52
	v_lshlrev_b32_e32 v16, 16, v108
	v_and_b32_e32 v17, 0xffff0000, v108
	v_lshlrev_b32_e32 v18, 16, v109
	v_and_b32_e32 v19, 0xffff0000, v109
	v_lshlrev_b32_e32 v20, 16, v110
	v_and_b32_e32 v21, 0xffff0000, v110
	v_lshlrev_b32_e32 v22, 16, v111
	v_and_b32_e32 v23, 0xffff0000, v111
	s_and_saveexec_b64 s[26:27], vcc
	v_pk_add_f32 v[32:33], v[32:33], v[16:17] neg_lo:[0,1] neg_hi:[0,1]
	v_pk_add_f32 v[34:35], v[34:35], v[18:19] neg_lo:[0,1] neg_hi:[0,1]
	v_pk_add_f32 v[36:37], v[36:37], v[20:21] neg_lo:[0,1] neg_hi:[0,1]
	v_pk_add_f32 v[38:39], v[38:39], v[22:23] neg_lo:[0,1] neg_hi:[0,1]
	s_or_b64 exec, exec, s[26:27]
	v_min_u32_e32 v40, s15, v52
	v_cvt_f32_ubyte0_e32 v40, v40
	v_div_scale_f32 v41, s[26:27], v40, v40, 1.0
	v_rcp_f32_e32 v42, v41
	v_div_scale_f32 v43, vcc, 1.0, v40, 1.0
	v_fma_f32 v44, -v41, v42, 1.0
	v_fmac_f32_e32 v42, v44, v42
	v_mul_f32_e32 v44, v43, v42
	v_fma_f32 v45, -v41, v44, v43
	v_fmac_f32_e32 v44, v45, v42
	v_fma_f32 v41, -v41, v44, v43
	v_div_fmas_f32 v41, v41, v42, v44
	v_div_fixup_f32 v40, v41, v40, 1.0
	v_fma_f32 v46, v40, v32, -v8
	v_fma_f32 v47, v40, v33, -v9
	v_cvt_pk_bf16_f32 v24, v46, v47
	v_fma_f32 v46, v40, v34, -v10
	v_fma_f32 v47, v40, v35, -v11
	v_cvt_pk_bf16_f32 v25, v46, v47
	v_fma_f32 v46, v40, v36, -v12
	v_fma_f32 v47, v40, v37, -v13
	v_cvt_pk_bf16_f32 v26, v46, v47
	v_fma_f32 v46, v40, v38, -v14
	v_fma_f32 v47, v40, v39, -v15
	v_cvt_pk_bf16_f32 v27, v46, v47
	global_store_dwordx4 v[28:29], v[24:27], off offset:2048
	s_nop 1
	s_waitcnt vmcnt(24)
	v_lshlrev_b32_e32 v8, 16, v112
	v_and_b32_e32 v9, 0xffff0000, v112
	v_lshlrev_b32_e32 v10, 16, v113
	v_and_b32_e32 v11, 0xffff0000, v113
	v_lshlrev_b32_e32 v12, 16, v114
	v_and_b32_e32 v13, 0xffff0000, v114
	v_lshlrev_b32_e32 v14, 16, v115
	v_and_b32_e32 v15, 0xffff0000, v115
	v_pk_add_f32 v[32:33], v[32:33], v[8:9]
	v_pk_add_f32 v[34:35], v[34:35], v[10:11]
	v_pk_add_f32 v[36:37], v[36:37], v[12:13]
	v_pk_add_f32 v[38:39], v[38:39], v[14:15]
	s_add_i32 s20, s14, 6
	s_add_i32 s15, s20, 1
	v_cmp_ge_u32_e32 vcc, s20, v52
	v_lshlrev_b32_e32 v16, 16, v116
	v_and_b32_e32 v17, 0xffff0000, v116
	v_lshlrev_b32_e32 v18, 16, v117
	v_and_b32_e32 v19, 0xffff0000, v117
	v_lshlrev_b32_e32 v20, 16, v118
	v_and_b32_e32 v21, 0xffff0000, v118
	v_lshlrev_b32_e32 v22, 16, v119
	v_and_b32_e32 v23, 0xffff0000, v119
	s_and_saveexec_b64 s[26:27], vcc
	v_pk_add_f32 v[32:33], v[32:33], v[16:17] neg_lo:[0,1] neg_hi:[0,1]
	v_pk_add_f32 v[34:35], v[34:35], v[18:19] neg_lo:[0,1] neg_hi:[0,1]
	v_pk_add_f32 v[36:37], v[36:37], v[20:21] neg_lo:[0,1] neg_hi:[0,1]
	v_pk_add_f32 v[38:39], v[38:39], v[22:23] neg_lo:[0,1] neg_hi:[0,1]
	s_or_b64 exec, exec, s[26:27]
	v_min_u32_e32 v40, s15, v52
	v_cvt_f32_ubyte0_e32 v40, v40
	v_div_scale_f32 v41, s[26:27], v40, v40, 1.0
	v_rcp_f32_e32 v42, v41
	v_div_scale_f32 v43, vcc, 1.0, v40, 1.0
	v_fma_f32 v44, -v41, v42, 1.0
	v_fmac_f32_e32 v42, v44, v42
	v_mul_f32_e32 v44, v43, v42
	v_fma_f32 v45, -v41, v44, v43
	v_fmac_f32_e32 v44, v45, v42
	v_fma_f32 v41, -v41, v44, v43
	v_div_fmas_f32 v41, v41, v42, v44
	v_div_fixup_f32 v40, v41, v40, 1.0
	v_fma_f32 v46, v40, v32, -v8
	v_fma_f32 v47, v40, v33, -v9
	v_cvt_pk_bf16_f32 v24, v46, v47
	v_fma_f32 v46, v40, v34, -v10
	v_fma_f32 v47, v40, v35, -v11
	v_cvt_pk_bf16_f32 v25, v46, v47
	v_fma_f32 v46, v40, v36, -v12
	v_fma_f32 v47, v40, v37, -v13
	v_cvt_pk_bf16_f32 v26, v46, v47
	v_fma_f32 v46, v40, v38, -v14
	v_fma_f32 v47, v40, v39, -v15
	v_cvt_pk_bf16_f32 v27, v46, v47
	v_add_co_u32_e32 v28, vcc, 0x3000, v56
	s_nop 1
	v_addc_co_u32_e32 v29, vcc, 0, v57, vcc
	global_store_dwordx4 v[28:29], v[24:27], off
	s_waitcnt vmcnt(23)
; __device__ __forceinline__ float bf_lo(unsigned w) { return __uint_as_float(w << 16); }
; __device__ __forceinline__ float bf_hi(unsigned w) { return __uint_as_float(w & 0xffff0000u); }
; __device__ __forceinline__ unsigned pk2(float lo, float hi) { return pg8::cvt_pk_bf16(lo, hi); }
; __global__ void __launch_bounds__(NWAVES * 64, 2) trunk_fwd(Args args) {
;     ...
;                 for (int i0 = 0; i0 < 32; i0 += 4) {
;                     v4u qq[4], oo[4];
; #pragma unroll
;                     for (int k = 0; k < 4; ++k) { qq[k] = *(const v4u*)(up + (size_t)(i0 + k) * 2048); oo[k] = *(const v4u*)(up + ((long)(i0 + k) - w) * 2048); }
; #pragma unroll
;                     for (int k = 0; k < 4; ++k) { const int i = i0 + k; const v4u q = qq[k], o = oo[k];
;                     float cur[8] = {bf_lo(q.x), bf_hi(q.x), bf_lo(q.y), bf_hi(q.y), bf_lo(q.z), bf_hi(q.z), bf_lo(q.w), bf_hi(q.w)};
; #pragma unroll
;                     for (int e = 0; e < 8; ++e) sum[e] += cur[e];
;                     const int t = t0 + i;
;                     if (t - w >= 0) {
;                         sum[0] -= bf_lo(o.x); sum[1] -= bf_hi(o.x); sum[2] -= bf_lo(o.y); sum[3] -= bf_hi(o.y); sum[4] -= bf_lo(o.z); sum[5] -= bf_hi(o.z); sum[6] -= bf_lo(o.w); sum[7] -= bf_hi(o.w); }
;                     const float rc = 1.0f / (float)((t + 1) < w ? (t + 1) : w);
;                     v4u r; r.x = pk2(sum[0] * rc - cur[0], sum[1] * rc - cur[1]); r.y = pk2(sum[2] * rc - cur[2], sum[3] * rc - cur[3]); r.z = pk2(sum[4] * rc - cur[4], sum[5] * rc - cur[5]); r.w = pk2(sum[6] * rc - cur[6], sum[7] * rc - cur[7]);
;                     *(v4u*)(op + (size_t)i * 1024) = r; }
	v_lshlrev_b32_e32 v8, 16, v120
	v_and_b32_e32 v9, 0xffff0000, v120
	v_lshlrev_b32_e32 v10, 16, v121
	v_and_b32_e32 v11, 0xffff0000, v121
	v_lshlrev_b32_e32 v12, 16, v122
	v_and_b32_e32 v13, 0xffff0000, v122
	v_lshlrev_b32_e32 v14, 16, v123
	v_and_b32_e32 v15, 0xffff0000, v123
	v_pk_add_f32 v[32:33], v[32:33], v[8:9]
	v_pk_add_f32 v[34:35], v[34:35], v[10:11]
	v_pk_add_f32 v[36:37], v[36:37], v[12:13]
	v_pk_add_f32 v[38:39], v[38:39], v[14:15]
	s_add_i32 s20, s14, 7
	s_add_i32 s15, s20, 1
	v_cmp_ge_u32_e32 vcc, s20, v52
	v_lshlrev_b32_e32 v16, 16, v124
	v_and_b32_e32 v17, 0xffff0000, v124
	v_lshlrev_b32_e32 v18, 16, v125
	v_and_b32_e32 v19, 0xffff0000, v125
	v_lshlrev_b32_e32 v20, 16, v126
	v_and_b32_e32 v21, 0xffff0000, v126
	v_lshlrev_b32_e32 v22, 16, v127
	v_and_b32_e32 v23, 0xffff0000, v127
	s_and_saveexec_b64 s[26:27], vcc
	v_pk_add_f32 v[32:33], v[32:33], v[16:17] neg_lo:[0,1] neg_hi:[0,1]
	v_pk_add_f32 v[34:35], v[34:35], v[18:19] neg_lo:[0,1] neg_hi:[0,1]
	v_pk_add_f32 v[36:37], v[36:37], v[20:21] neg_lo:[0,1] neg_hi:[0,1]
	v_pk_add_f32 v[38:39], v[38:39], v[22:23] neg_lo:[0,1] neg_hi:[0,1]
	s_or_b64 exec, exec, s[26:27]
	v_min_u32_e32 v40, s15, v52
	v_cvt_f32_ubyte0_e32 v40, v40
	v_div_scale_f32 v41, s[26:27], v40, v40, 1.0
	v_rcp_f32_e32 v42, v41
	v_div_scale_f32 v43, vcc, 1.0, v40, 1.0
	v_fma_f32 v44, -v41, v42, 1.0
	v_fmac_f32_e32 v42, v44, v42
	v_mul_f32_e32 v44, v43, v42
	v_fma_f32 v45, -v41, v44, v43
	v_fmac_f32_e32 v44, v45, v42
	v_fma_f32 v41, -v41, v44, v43
	v_div_fmas_f32 v41, v41, v42, v44
	v_div_fixup_f32 v40, v41, v40, 1.0
	v_fma_f32 v46, v40, v32, -v8
	v_fma_f32 v47, v40, v33, -v9
	v_cvt_pk_bf16_f32 v24, v46, v47
	v_fma_f32 v46, v40, v34, -v10
	v_fma_f32 v47, v40, v35, -v11
	v_cvt_pk_bf16_f32 v25, v46, v47
	v_fma_f32 v46, v40, v36, -v12
	v_fma_f32 v47, v40, v37, -v13
	v_cvt_pk_bf16_f32 v26, v46, v47
	v_fma_f32 v46, v40, v38, -v14
	v_fma_f32 v47, v40, v39, -v15
	v_cvt_pk_bf16_f32 v27, v46, v47
	global_store_dwordx4 v[28:29], v[24:27], off offset:2048
	s_nop 1
	v_add_co_u32_e32 v4, vcc, 0x11000, v58
	s_nop 1
	v_addc_co_u32_e32 v5, vcc, 0, v59, vcc
	v_add_co_u32_e32 v6, vcc, 0x11000, v62
	s_nop 1
	v_addc_co_u32_e32 v7, vcc, 0, v63, vcc
	global_load_dwordx4 v[64:67], v[4:5], off offset:-4096
	global_load_dwordx4 v[68:71], v[6:7], off offset:-4096
	global_load_dwordx4 v[72:75], v[4:5], off
	global_load_dwordx4 v[76:79], v[6:7], off
	v_add_co_u32_e32 v4, vcc, 0x13000, v58
	s_nop 1
	v_addc_co_u32_e32 v5, vcc, 0, v59, vcc
	v_add_co_u32_e32 v6, vcc, 0x13000, v62
	s_nop 1
	v_addc_co_u32_e32 v7, vcc, 0, v63, vcc
	global_load_dwordx4 v[80:83], v[4:5], off offset:-4096
	global_load_dwordx4 v[84:87], v[6:7], off offset:-4096
	global_load_dwordx4 v[88:91], v[4:5], off
	global_load_dwordx4 v[92:95], v[6:7], off
	v_add_co_u32_e32 v4, vcc, 0x15000, v58
	s_nop 1
	v_addc_co_u32_e32 v5, vcc, 0, v59, vcc
	v_add_co_u32_e32 v6, vcc, 0x15000, v62
	s_nop 1
	v_addc_co_u32_e32 v7, vcc, 0, v63, vcc
	global_load_dwordx4 v[96:99], v[4:5], off offset:-4096
	global_load_dwordx4 v[100:103], v[6:7], off offset:-4096
	global_load_dwordx4 v[104:107], v[4:5], off
	global_load_dwordx4 v[108:111], v[6:7], off
	v_add_co_u32_e32 v4, vcc, 0x17000, v58
	s_nop 1
	v_addc_co_u32_e32 v5, vcc, 0, v59, vcc
	v_add_co_u32_e32 v6, vcc, 0x17000, v62
	s_nop 1
	v_addc_co_u32_e32 v7, vcc, 0, v63, vcc
	global_load_dwordx4 v[112:115], v[4:5], off offset:-4096
	global_load_dwordx4 v[116:119], v[6:7], off offset:-4096
	global_load_dwordx4 v[120:123], v[4:5], off
	global_load_dwordx4 v[124:127], v[6:7], off
	s_waitcnt vmcnt(38)
	v_lshlrev_b32_e32 v8, 16, v128
	v_and_b32_e32 v9, 0xffff0000, v128
	v_lshlrev_b32_e32 v10, 16, v129
	v_and_b32_e32 v11, 0xffff0000, v129
	v_lshlrev_b32_e32 v12, 16, v130
	v_and_b32_e32 v13, 0xffff0000, v130
	v_lshlrev_b32_e32 v14, 16, v131
	v_and_b32_e32 v15, 0xffff0000, v131
	v_pk_add_f32 v[32:33], v[32:33], v[8:9]
	v_pk_add_f32 v[34:35], v[34:35], v[10:11]
	v_pk_add_f32 v[36:37], v[36:37], v[12:13]
	v_pk_add_f32 v[38:39], v[38:39], v[14:15]
	s_add_i32 s20, s14, 8
	s_add_i32 s15, s20, 1
	v_cmp_ge_u32_e32 vcc, s20, v52
	v_lshlrev_b32_e32 v16, 16, v132
	v_and_b32_e32 v17, 0xffff0000, v132
	v_lshlrev_b32_e32 v18, 16, v133
	v_and_b32_e32 v19, 0xffff0000, v133
	v_lshlrev_b32_e32 v20, 16, v134
	v_and_b32_e32 v21, 0xffff0000, v134
	v_lshlrev_b32_e32 v22, 16, v135
	v_and_b32_e32 v23, 0xffff0000, v135
	s_and_saveexec_b64 s[26:27], vcc
	v_pk_add_f32 v[32:33], v[32:33], v[16:17] neg_lo:[0,1] neg_hi:[0,1]
	v_pk_add_f32 v[34:35], v[34:35], v[18:19] neg_lo:[0,1] neg_hi:[0,1]
	v_pk_add_f32 v[36:37], v[36:37], v[20:21] neg_lo:[0,1] neg_hi:[0,1]
	v_pk_add_f32 v[38:39], v[38:39], v[22:23] neg_lo:[0,1] neg_hi:[0,1]
	s_or_b64 exec, exec, s[26:27]
	v_min_u32_e32 v40, s15, v52
	v_cvt_f32_ubyte0_e32 v40, v40
	v_div_scale_f32 v41, s[26:27], v40, v40, 1.0
	v_rcp_f32_e32 v42, v41
	v_div_scale_f32 v43, vcc, 1.0, v40, 1.0
	v_fma_f32 v44, -v41, v42, 1.0
	v_fmac_f32_e32 v42, v44, v42
	v_mul_f32_e32 v44, v43, v42
	v_fma_f32 v45, -v41, v44, v43
	v_fmac_f32_e32 v44, v45, v42
	v_fma_f32 v41, -v41, v44, v43
	v_div_fmas_f32 v41, v41, v42, v44
	v_div_fixup_f32 v40, v41, v40, 1.0
	v_fma_f32 v46, v40, v32, -v8
	v_fma_f32 v47, v40, v33, -v9
	v_cvt_pk_bf16_f32 v24, v46, v47
	v_fma_f32 v46, v40, v34, -v10
	v_fma_f32 v47, v40, v35, -v11
	v_cvt_pk_bf16_f32 v25, v46, v47
	v_fma_f32 v46, v40, v36, -v12
	v_fma_f32 v47, v40, v37, -v13
	v_cvt_pk_bf16_f32 v26, v46, v47
	v_fma_f32 v46, v40, v38, -v14
	v_fma_f32 v47, v40, v39, -v15
	v_cvt_pk_bf16_f32 v27, v46, v47
	v_add_co_u32_e32 v28, vcc, 0x4000, v56
	s_nop 1
	v_addc_co_u32_e32 v29, vcc, 0, v57, vcc
	global_store_dwordx4 v[28:29], v[24:27], off
	s_waitcnt vmcnt(37)
; __device__ __forceinline__ float bf_lo(unsigned w) { return __uint_as_float(w << 16); }
; __device__ __forceinline__ float bf_hi(unsigned w) { return __uint_as_float(w & 0xffff0000u); }
; __device__ __forceinline__ unsigned pk2(float lo, float hi) { return pg8::cvt_pk_bf16(lo, hi); }
; __global__ void __launch_bounds__(NWAVES * 64, 2) trunk_fwd(Args args) {
;     ...
;                 for (int i0 = 0; i0 < 32; i0 += 4) {
;                     v4u qq[4], oo[4];
; #pragma unroll
;                     for (int k = 0; k < 4; ++k) { qq[k] = *(const v4u*)(up + (size_t)(i0 + k) * 2048); oo[k] = *(const v4u*)(up + ((long)(i0 + k) - w) * 2048); }
; #pragma unroll
;                     for (int k = 0; k < 4; ++k) { const int i = i0 + k; const v4u q = qq[k], o = oo[k];
;                     float cur[8] = {bf_lo(q.x), bf_hi(q.x), bf_lo(q.y), bf_hi(q.y), bf_lo(q.z), bf_hi(q.z), bf_lo(q.w), bf_hi(q.w)};
; #pragma unroll
;                     for (int e = 0; e < 8; ++e) sum[e] += cur[e];
;                     const int t = t0 + i;
;                     if (t - w >= 0) {
;                         sum[0] -= bf_lo(o.x); sum[1] -= bf_hi(o.x); sum[2] -= bf_lo(o.y); sum[3] -= bf_hi(o.y); sum[4] -= bf_lo(o.z); sum[5] -= bf_hi(o.z); sum[6] -= bf_lo(o.w); sum[7] -= bf_hi(o.w); }
;                     const float rc = 1.0f / (float)((t + 1) < w ? (t + 1) : w);
;                     v4u r; r.x = pk2(sum[0] * rc - cur[0], sum[1] * rc - cur[1]); r.y = pk2(sum[2] * rc - cur[2], sum[3] * rc - cur[3]); r.z = pk2(sum[4] * rc - cur[4], sum[5] * rc - cur[5]); r.w = pk2(sum[6] * rc - cur[6], sum[7] * rc - cur[7]);
;                     *(v4u*)(op + (size_t)i * 1024) = r; }
	v_lshlrev_b32_e32 v8, 16, v136
	v_and_b32_e32 v9, 0xffff0000, v136
	v_lshlrev_b32_e32 v10, 16, v137
	v_and_b32_e32 v11, 0xffff0000, v137
	v_lshlrev_b32_e32 v12, 16, v138
	v_and_b32_e32 v13, 0xffff0000, v138
	v_lshlrev_b32_e32 v14, 16, v139
	v_and_b32_e32 v15, 0xffff0000, v139
	v_pk_add_f32 v[32:33], v[32:33], v[8:9]
	v_pk_add_f32 v[34:35], v[34:35], v[10:11]
	v_pk_add_f32 v[36:37], v[36:37], v[12:13]
	v_pk_add_f32 v[38:39], v[38:39], v[14:15]
	s_add_i32 s20, s14, 9
	s_add_i32 s15, s20, 1
	v_cmp_ge_u32_e32 vcc, s20, v52
	v_lshlrev_b32_e32 v16, 16, v140
	v_and_b32_e32 v17, 0xffff0000, v140
	v_lshlrev_b32_e32 v18, 16, v141
	v_and_b32_e32 v19, 0xffff0000, v141
	v_lshlrev_b32_e32 v20, 16, v142
	v_and_b32_e32 v21, 0xffff0000, v142
	v_lshlrev_b32_e32 v22, 16, v143
	v_and_b32_e32 v23, 0xffff0000, v143
	s_and_saveexec_b64 s[26:27], vcc
	v_pk_add_f32 v[32:33], v[32:33], v[16:17] neg_lo:[0,1] neg_hi:[0,1]
	v_pk_add_f32 v[34:35], v[34:35], v[18:19] neg_lo:[0,1] neg_hi:[0,1]
	v_pk_add_f32 v[36:37], v[36:37], v[20:21] neg_lo:[0,1] neg_hi:[0,1]
	v_pk_add_f32 v[38:39], v[38:39], v[22:23] neg_lo:[0,1] neg_hi:[0,1]
	s_or_b64 exec, exec, s[26:27]
	v_min_u32_e32 v40, s15, v52
	v_cvt_f32_ubyte0_e32 v40, v40
	v_div_scale_f32 v41, s[26:27], v40, v40, 1.0
	v_rcp_f32_e32 v42, v41
	v_div_scale_f32 v43, vcc, 1.0, v40, 1.0
	v_fma_f32 v44, -v41, v42, 1.0
	v_fmac_f32_e32 v42, v44, v42
	v_mul_f32_e32 v44, v43, v42
	v_fma_f32 v45, -v41, v44, v43
	v_fmac_f32_e32 v44, v45, v42
	v_fma_f32 v41, -v41, v44, v43
	v_div_fmas_f32 v41, v41, v42, v44
	v_div_fixup_f32 v40, v41, v40, 1.0
	v_fma_f32 v46, v40, v32, -v8
	v_fma_f32 v47, v40, v33, -v9
	v_cvt_pk_bf16_f32 v24, v46, v47
	v_fma_f32 v46, v40, v34, -v10
	v_fma_f32 v47, v40, v35, -v11
	v_cvt_pk_bf16_f32 v25, v46, v47
	v_fma_f32 v46, v40, v36, -v12
	v_fma_f32 v47, v40, v37, -v13
	v_cvt_pk_bf16_f32 v26, v46, v47
	v_fma_f32 v46, v40, v38, -v14
	v_fma_f32 v47, v40, v39, -v15
	v_cvt_pk_bf16_f32 v27, v46, v47
	global_store_dwordx4 v[28:29], v[24:27], off offset:2048
	s_nop 1
	s_waitcnt vmcnt(36)
	v_lshlrev_b32_e32 v8, 16, v144
	v_and_b32_e32 v9, 0xffff0000, v144
	v_lshlrev_b32_e32 v10, 16, v145
	v_and_b32_e32 v11, 0xffff0000, v145
	v_lshlrev_b32_e32 v12, 16, v146
	v_and_b32_e32 v13, 0xffff0000, v146
	v_lshlrev_b32_e32 v14, 16, v147
	v_and_b32_e32 v15, 0xffff0000, v147
	v_pk_add_f32 v[32:33], v[32:33], v[8:9]
	v_pk_add_f32 v[34:35], v[34:35], v[10:11]
	v_pk_add_f32 v[36:37], v[36:37], v[12:13]
	v_pk_add_f32 v[38:39], v[38:39], v[14:15]
	s_add_i32 s20, s14, 10
	s_add_i32 s15, s20, 1
	v_cmp_ge_u32_e32 vcc, s20, v52
	v_lshlrev_b32_e32 v16, 16, v148
	v_and_b32_e32 v17, 0xffff0000, v148
	v_lshlrev_b32_e32 v18, 16, v149
	v_and_b32_e32 v19, 0xffff0000, v149
	v_lshlrev_b32_e32 v20, 16, v150
	v_and_b32_e32 v21, 0xffff0000, v150
	v_lshlrev_b32_e32 v22, 16, v151
	v_and_b32_e32 v23, 0xffff0000, v151
	s_and_saveexec_b64 s[26:27], vcc
	v_pk_add_f32 v[32:33], v[32:33], v[16:17] neg_lo:[0,1] neg_hi:[0,1]
	v_pk_add_f32 v[34:35], v[34:35], v[18:19] neg_lo:[0,1] neg_hi:[0,1]
	v_pk_add_f32 v[36:37], v[36:37], v[20:21] neg_lo:[0,1] neg_hi:[0,1]
	v_pk_add_f32 v[38:39], v[38:39], v[22:23] neg_lo:[0,1] neg_hi:[0,1]
	s_or_b64 exec, exec, s[26:27]
	v_min_u32_e32 v40, s15, v52
	v_cvt_f32_ubyte0_e32 v40, v40
	v_div_scale_f32 v41, s[26:27], v40, v40, 1.0
	v_rcp_f32_e32 v42, v41
	v_div_scale_f32 v43, vcc, 1.0, v40, 1.0
	v_fma_f32 v44, -v41, v42, 1.0
	v_fmac_f32_e32 v42, v44, v42
	v_mul_f32_e32 v44, v43, v42
	v_fma_f32 v45, -v41, v44, v43
	v_fmac_f32_e32 v44, v45, v42
	v_fma_f32 v41, -v41, v44, v43
	v_div_fmas_f32 v41, v41, v42, v44
	v_div_fixup_f32 v40, v41, v40, 1.0
	v_fma_f32 v46, v40, v32, -v8
	v_fma_f32 v47, v40, v33, -v9
	v_cvt_pk_bf16_f32 v24, v46, v47
	v_fma_f32 v46, v40, v34, -v10
	v_fma_f32 v47, v40, v35, -v11
	v_cvt_pk_bf16_f32 v25, v46, v47
	v_fma_f32 v46, v40, v36, -v12
	v_fma_f32 v47, v40, v37, -v13
	v_cvt_pk_bf16_f32 v26, v46, v47
	v_fma_f32 v46, v40, v38, -v14
	v_fma_f32 v47, v40, v39, -v15
	v_cvt_pk_bf16_f32 v27, v46, v47
	v_add_co_u32_e32 v28, vcc, 0x5000, v56
	s_nop 1
	v_addc_co_u32_e32 v29, vcc, 0, v57, vcc
	global_store_dwordx4 v[28:29], v[24:27], off
	s_waitcnt vmcnt(35)
	v_lshlrev_b32_e32 v8, 16, v152
	v_and_b32_e32 v9, 0xffff0000, v152
	v_lshlrev_b32_e32 v10, 16, v153
	v_and_b32_e32 v11, 0xffff0000, v153
	v_lshlrev_b32_e32 v12, 16, v154
	v_and_b32_e32 v13, 0xffff0000, v154
	v_lshlrev_b32_e32 v14, 16, v155
	v_and_b32_e32 v15, 0xffff0000, v155
	v_pk_add_f32 v[32:33], v[32:33], v[8:9]
	v_pk_add_f32 v[34:35], v[34:35], v[10:11]
	v_pk_add_f32 v[36:37], v[36:37], v[12:13]
	v_pk_add_f32 v[38:39], v[38:39], v[14:15]
	s_add_i32 s20, s14, 11
	s_add_i32 s15, s20, 1
	v_cmp_ge_u32_e32 vcc, s20, v52
	v_lshlrev_b32_e32 v16, 16, v156
	v_and_b32_e32 v17, 0xffff0000, v156
	v_lshlrev_b32_e32 v18, 16, v157
	v_and_b32_e32 v19, 0xffff0000, v157
	v_lshlrev_b32_e32 v20, 16, v158
	v_and_b32_e32 v21, 0xffff0000, v158
	v_lshlrev_b32_e32 v22, 16, v159
	v_and_b32_e32 v23, 0xffff0000, v159
	s_and_saveexec_b64 s[26:27], vcc
	v_pk_add_f32 v[32:33], v[32:33], v[16:17] neg_lo:[0,1] neg_hi:[0,1]
	v_pk_add_f32 v[34:35], v[34:35], v[18:19] neg_lo:[0,1] neg_hi:[0,1]
	v_pk_add_f32 v[36:37], v[36:37], v[20:21] neg_lo:[0,1] neg_hi:[0,1]
	v_pk_add_f32 v[38:39], v[38:39], v[22:23] neg_lo:[0,1] neg_hi:[0,1]
	s_or_b64 exec, exec, s[26:27]
	v_min_u32_e32 v40, s15, v52
	v_cvt_f32_ubyte0_e32 v40, v40
	v_div_scale_f32 v41, s[26:27], v40, v40, 1.0
	v_rcp_f32_e32 v42, v41
	v_div_scale_f32 v43, vcc, 1.0, v40, 1.0
	v_fma_f32 v44, -v41, v42, 1.0
	v_fmac_f32_e32 v42, v44, v42
	v_mul_f32_e32 v44, v43, v42
	v_fma_f32 v45, -v41, v44, v43
	v_fmac_f32_e32 v44, v45, v42
	v_fma_f32 v41, -v41, v44, v43
	v_div_fmas_f32 v41, v41, v42, v44
	v_div_fixup_f32 v40, v41, v40, 1.0
	v_fma_f32 v46, v40, v32, -v8
	v_fma_f32 v47, v40, v33, -v9
	v_cvt_pk_bf16_f32 v24, v46, v47
	v_fma_f32 v46, v40, v34, -v10
	v_fma_f32 v47, v40, v35, -v11
	v_cvt_pk_bf16_f32 v25, v46, v47
	v_fma_f32 v46, v40, v36, -v12
	v_fma_f32 v47, v40, v37, -v13
	v_cvt_pk_bf16_f32 v26, v46, v47
	v_fma_f32 v46, v40, v38, -v14
	v_fma_f32 v47, v40, v39, -v15
	v_cvt_pk_bf16_f32 v27, v46, v47
	global_store_dwordx4 v[28:29], v[24:27], off offset:2048
	s_nop 1
	s_waitcnt vmcnt(34)
; __device__ __forceinline__ float bf_lo(unsigned w) { return __uint_as_float(w << 16); }
; __device__ __forceinline__ float bf_hi(unsigned w) { return __uint_as_float(w & 0xffff0000u); }
; __device__ __forceinline__ unsigned pk2(float lo, float hi) { return pg8::cvt_pk_bf16(lo, hi); }
; __global__ void __launch_bounds__(NWAVES * 64, 2) trunk_fwd(Args args) {
;     ...
;                 for (int i0 = 0; i0 < 32; i0 += 4) {
;                     v4u qq[4], oo[4];
; #pragma unroll
;                     for (int k = 0; k < 4; ++k) { qq[k] = *(const v4u*)(up + (size_t)(i0 + k) * 2048); oo[k] = *(const v4u*)(up + ((long)(i0 + k) - w) * 2048); }
; #pragma unroll
;                     for (int k = 0; k < 4; ++k) { const int i = i0 + k; const v4u q = qq[k], o = oo[k];
;                     float cur[8] = {bf_lo(q.x), bf_hi(q.x), bf_lo(q.y), bf_hi(q.y), bf_lo(q.z), bf_hi(q.z), bf_lo(q.w), bf_hi(q.w)};
; #pragma unroll
;                     for (int e = 0; e < 8; ++e) sum[e] += cur[e];
;                     const int t = t0 + i;
;                     if (t - w >= 0) {
;                         sum[0] -= bf_lo(o.x); sum[1] -= bf_hi(o.x); sum[2] -= bf_lo(o.y); sum[3] -= bf_hi(o.y); sum[4] -= bf_lo(o.z); sum[5] -= bf_hi(o.z); sum[6] -= bf_lo(o.w); sum[7] -= bf_hi(o.w); }
;                     const float rc = 1.0f / (float)((t + 1) < w ? (t + 1) : w);
;                     v4u r; r.x = pk2(sum[0] * rc - cur[0], sum[1] * rc - cur[1]); r.y = pk2(sum[2] * rc - cur[2], sum[3] * rc - cur[3]); r.z = pk2(sum[4] * rc - cur[4], sum[5] * rc - cur[5]); r.w = pk2(sum[6] * rc - cur[6], sum[7] * rc - cur[7]);
;                     *(v4u*)(op + (size_t)i * 1024) = r; }
	v_lshlrev_b32_e32 v8, 16, v160
	v_and_b32_e32 v9, 0xffff0000, v160
	v_lshlrev_b32_e32 v10, 16, v161
	v_and_b32_e32 v11, 0xffff0000, v161
	v_lshlrev_b32_e32 v12, 16, v162
	v_and_b32_e32 v13, 0xffff0000, v162
	v_lshlrev_b32_e32 v14, 16, v163
	v_and_b32_e32 v15, 0xffff0000, v163
	v_pk_add_f32 v[32:33], v[32:33], v[8:9]
	v_pk_add_f32 v[34:35], v[34:35], v[10:11]
	v_pk_add_f32 v[36:37], v[36:37], v[12:13]
	v_pk_add_f32 v[38:39], v[38:39], v[14:15]
	s_add_i32 s20, s14, 12
	s_add_i32 s15, s20, 1
	v_cmp_ge_u32_e32 vcc, s20, v52
	v_lshlrev_b32_e32 v16, 16, v164
	v_and_b32_e32 v17, 0xffff0000, v164
	v_lshlrev_b32_e32 v18, 16, v165
	v_and_b32_e32 v19, 0xffff0000, v165
	v_lshlrev_b32_e32 v20, 16, v166
	v_and_b32_e32 v21, 0xffff0000, v166
	v_lshlrev_b32_e32 v22, 16, v167
	v_and_b32_e32 v23, 0xffff0000, v167
	s_and_saveexec_b64 s[26:27], vcc
	v_pk_add_f32 v[32:33], v[32:33], v[16:17] neg_lo:[0,1] neg_hi:[0,1]
	v_pk_add_f32 v[34:35], v[34:35], v[18:19] neg_lo:[0,1] neg_hi:[0,1]
	v_pk_add_f32 v[36:37], v[36:37], v[20:21] neg_lo:[0,1] neg_hi:[0,1]
	v_pk_add_f32 v[38:39], v[38:39], v[22:23] neg_lo:[0,1] neg_hi:[0,1]
	s_or_b64 exec, exec, s[26:27]
	v_min_u32_e32 v40, s15, v52
	v_cvt_f32_ubyte0_e32 v40, v40
	v_div_scale_f32 v41, s[26:27], v40, v40, 1.0
	v_rcp_f32_e32 v42, v41
	v_div_scale_f32 v43, vcc, 1.0, v40, 1.0
	v_fma_f32 v44, -v41, v42, 1.0
	v_fmac_f32_e32 v42, v44, v42
	v_mul_f32_e32 v44, v43, v42
	v_fma_f32 v45, -v41, v44, v43
	v_fmac_f32_e32 v44, v45, v42
	v_fma_f32 v41, -v41, v44, v43
	v_div_fmas_f32 v41, v41, v42, v44
	v_div_fixup_f32 v40, v41, v40, 1.0
	v_fma_f32 v46, v40, v32, -v8
	v_fma_f32 v47, v40, v33, -v9
	v_cvt_pk_bf16_f32 v24, v46, v47
	v_fma_f32 v46, v40, v34, -v10
	v_fma_f32 v47, v40, v35, -v11
	v_cvt_pk_bf16_f32 v25, v46, v47
	v_fma_f32 v46, v40, v36, -v12
	v_fma_f32 v47, v40, v37, -v13
	v_cvt_pk_bf16_f32 v26, v46, v47
	v_fma_f32 v46, v40, v38, -v14
	v_fma_f32 v47, v40, v39, -v15
	v_cvt_pk_bf16_f32 v27, v46, v47
	v_add_co_u32_e32 v28, vcc, 0x6000, v56
	s_nop 1
	v_addc_co_u32_e32 v29, vcc, 0, v57, vcc
	global_store_dwordx4 v[28:29], v[24:27], off
	s_waitcnt vmcnt(33)
	v_lshlrev_b32_e32 v8, 16, v168
	v_and_b32_e32 v9, 0xffff0000, v168
	v_lshlrev_b32_e32 v10, 16, v169
	v_and_b32_e32 v11, 0xffff0000, v169
	v_lshlrev_b32_e32 v12, 16, v170
	v_and_b32_e32 v13, 0xffff0000, v170
	v_lshlrev_b32_e32 v14, 16, v171
	v_and_b32_e32 v15, 0xffff0000, v171
	v_pk_add_f32 v[32:33], v[32:33], v[8:9]
	v_pk_add_f32 v[34:35], v[34:35], v[10:11]
	v_pk_add_f32 v[36:37], v[36:37], v[12:13]
	v_pk_add_f32 v[38:39], v[38:39], v[14:15]
	s_add_i32 s20, s14, 13
	s_add_i32 s15, s20, 1
	v_cmp_ge_u32_e32 vcc, s20, v52
	v_lshlrev_b32_e32 v16, 16, v172
	v_and_b32_e32 v17, 0xffff0000, v172
	v_lshlrev_b32_e32 v18, 16, v173
	v_and_b32_e32 v19, 0xffff0000, v173
	v_lshlrev_b32_e32 v20, 16, v174
	v_and_b32_e32 v21, 0xffff0000, v174
	v_lshlrev_b32_e32 v22, 16, v175
	v_and_b32_e32 v23, 0xffff0000, v175
	s_and_saveexec_b64 s[26:27], vcc
	v_pk_add_f32 v[32:33], v[32:33], v[16:17] neg_lo:[0,1] neg_hi:[0,1]
	v_pk_add_f32 v[34:35], v[34:35], v[18:19] neg_lo:[0,1] neg_hi:[0,1]
	v_pk_add_f32 v[36:37], v[36:37], v[20:21] neg_lo:[0,1] neg_hi:[0,1]
	v_pk_add_f32 v[38:39], v[38:39], v[22:23] neg_lo:[0,1] neg_hi:[0,1]
	s_or_b64 exec, exec, s[26:27]
	v_min_u32_e32 v40, s15, v52
	v_cvt_f32_ubyte0_e32 v40, v40
	v_div_scale_f32 v41, s[26:27], v40, v40, 1.0
	v_rcp_f32_e32 v42, v41
	v_div_scale_f32 v43, vcc, 1.0, v40, 1.0
	v_fma_f32 v44, -v41, v42, 1.0
	v_fmac_f32_e32 v42, v44, v42
	v_mul_f32_e32 v44, v43, v42
	v_fma_f32 v45, -v41, v44, v43
	v_fmac_f32_e32 v44, v45, v42
	v_fma_f32 v41, -v41, v44, v43
	v_div_fmas_f32 v41, v41, v42, v44
	v_div_fixup_f32 v40, v41, v40, 1.0
	v_fma_f32 v46, v40, v32, -v8
	v_fma_f32 v47, v40, v33, -v9
	v_cvt_pk_bf16_f32 v24, v46, v47
	v_fma_f32 v46, v40, v34, -v10
	v_fma_f32 v47, v40, v35, -v11
	v_cvt_pk_bf16_f32 v25, v46, v47
	v_fma_f32 v46, v40, v36, -v12
	v_fma_f32 v47, v40, v37, -v13
	v_cvt_pk_bf16_f32 v26, v46, v47
	v_fma_f32 v46, v40, v38, -v14
	v_fma_f32 v47, v40, v39, -v15
	v_cvt_pk_bf16_f32 v27, v46, v47
	global_store_dwordx4 v[28:29], v[24:27], off offset:2048
	s_nop 1
	s_waitcnt vmcnt(32)
	v_lshlrev_b32_e32 v8, 16, v176
	v_and_b32_e32 v9, 0xffff0000, v176
	v_lshlrev_b32_e32 v10, 16, v177
	v_and_b32_e32 v11, 0xffff0000, v177
	v_lshlrev_b32_e32 v12, 16, v178
	v_and_b32_e32 v13, 0xffff0000, v178
	v_lshlrev_b32_e32 v14, 16, v179
	v_and_b32_e32 v15, 0xffff0000, v179
	v_pk_add_f32 v[32:33], v[32:33], v[8:9]
	v_pk_add_f32 v[34:35], v[34:35], v[10:11]
	v_pk_add_f32 v[36:37], v[36:37], v[12:13]
	v_pk_add_f32 v[38:39], v[38:39], v[14:15]
	s_add_i32 s20, s14, 14
	s_add_i32 s15, s20, 1
	v_cmp_ge_u32_e32 vcc, s20, v52
	v_lshlrev_b32_e32 v16, 16, v180
	v_and_b32_e32 v17, 0xffff0000, v180
	v_lshlrev_b32_e32 v18, 16, v181
	v_and_b32_e32 v19, 0xffff0000, v181
	v_lshlrev_b32_e32 v20, 16, v182
	v_and_b32_e32 v21, 0xffff0000, v182
	v_lshlrev_b32_e32 v22, 16, v183
	v_and_b32_e32 v23, 0xffff0000, v183
	s_and_saveexec_b64 s[26:27], vcc
	v_pk_add_f32 v[32:33], v[32:33], v[16:17] neg_lo:[0,1] neg_hi:[0,1]
	v_pk_add_f32 v[34:35], v[34:35], v[18:19] neg_lo:[0,1] neg_hi:[0,1]
	v_pk_add_f32 v[36:37], v[36:37], v[20:21] neg_lo:[0,1] neg_hi:[0,1]
	v_pk_add_f32 v[38:39], v[38:39], v[22:23] neg_lo:[0,1] neg_hi:[0,1]
	s_or_b64 exec, exec, s[26:27]
	v_min_u32_e32 v40, s15, v52
	v_cvt_f32_ubyte0_e32 v40, v40
	v_div_scale_f32 v41, s[26:27], v40, v40, 1.0
	v_rcp_f32_e32 v42, v41
	v_div_scale_f32 v43, vcc, 1.0, v40, 1.0
	v_fma_f32 v44, -v41, v42, 1.0
	v_fmac_f32_e32 v42, v44, v42
	v_mul_f32_e32 v44, v43, v42
	v_fma_f32 v45, -v41, v44, v43
	v_fmac_f32_e32 v44, v45, v42
	v_fma_f32 v41, -v41, v44, v43
	v_div_fmas_f32 v41, v41, v42, v44
	v_div_fixup_f32 v40, v41, v40, 1.0
	v_fma_f32 v46, v40, v32, -v8
	v_fma_f32 v47, v40, v33, -v9
	v_cvt_pk_bf16_f32 v24, v46, v47
	v_fma_f32 v46, v40, v34, -v10
	v_fma_f32 v47, v40, v35, -v11
	v_cvt_pk_bf16_f32 v25, v46, v47
	v_fma_f32 v46, v40, v36, -v12
	v_fma_f32 v47, v40, v37, -v13
	v_cvt_pk_bf16_f32 v26, v46, v47
	v_fma_f32 v46, v40, v38, -v14
	v_fma_f32 v47, v40, v39, -v15
	v_cvt_pk_bf16_f32 v27, v46, v47
	v_add_co_u32_e32 v28, vcc, 0x7000, v56
	s_nop 1
	v_addc_co_u32_e32 v29, vcc, 0, v57, vcc
	global_store_dwordx4 v[28:29], v[24:27], off
	s_waitcnt vmcnt(31)
; __device__ __forceinline__ float bf_lo(unsigned w) { return __uint_as_float(w << 16); }
; __device__ __forceinline__ float bf_hi(unsigned w) { return __uint_as_float(w & 0xffff0000u); }
; __device__ __forceinline__ unsigned pk2(float lo, float hi) { return pg8::cvt_pk_bf16(lo, hi); }
; __global__ void __launch_bounds__(NWAVES * 64, 2) trunk_fwd(Args args) {
;     ...
;                 for (int i0 = 0; i0 < 32; i0 += 4) {
;                     v4u qq[4], oo[4];
; #pragma unroll
;                     for (int k = 0; k < 4; ++k) { qq[k] = *(const v4u*)(up + (size_t)(i0 + k) * 2048); oo[k] = *(const v4u*)(up + ((long)(i0 + k) - w) * 2048); }
; #pragma unroll
;                     for (int k = 0; k < 4; ++k) { const int i = i0 + k; const v4u q = qq[k], o = oo[k];
;                     float cur[8] = {bf_lo(q.x), bf_hi(q.x), bf_lo(q.y), bf_hi(q.y), bf_lo(q.z), bf_hi(q.z), bf_lo(q.w), bf_hi(q.w)};
; #pragma unroll
;                     for (int e = 0; e < 8; ++e) sum[e] += cur[e];
;                     const int t = t0 + i;
;                     if (t - w >= 0) {
;                         sum[0] -= bf_lo(o.x); sum[1] -= bf_hi(o.x); sum[2] -= bf_lo(o.y); sum[3] -= bf_hi(o.y); sum[4] -= bf_lo(o.z); sum[5] -= bf_hi(o.z); sum[6] -= bf_lo(o.w); sum[7] -= bf_hi(o.w); }
;                     const float rc = 1.0f / (float)((t + 1) < w ? (t + 1) : w);
;                     v4u r; r.x = pk2(sum[0] * rc - cur[0], sum[1] * rc - cur[1]); r.y = pk2(sum[2] * rc - cur[2], sum[3] * rc - cur[3]); r.z = pk2(sum[4] * rc - cur[4], sum[5] * rc - cur[5]); r.w = pk2(sum[6] * rc - cur[6], sum[7] * rc - cur[7]);
;                     *(v4u*)(op + (size_t)i * 1024) = r; }
	v_lshlrev_b32_e32 v8, 16, v184
	v_and_b32_e32 v9, 0xffff0000, v184
	v_lshlrev_b32_e32 v10, 16, v185
	v_and_b32_e32 v11, 0xffff0000, v185
	v_lshlrev_b32_e32 v12, 16, v186
	v_and_b32_e32 v13, 0xffff0000, v186
	v_lshlrev_b32_e32 v14, 16, v187
	v_and_b32_e32 v15, 0xffff0000, v187
	v_pk_add_f32 v[32:33], v[32:33], v[8:9]
	v_pk_add_f32 v[34:35], v[34:35], v[10:11]
	v_pk_add_f32 v[36:37], v[36:37], v[12:13]
	v_pk_add_f32 v[38:39], v[38:39], v[14:15]
	s_add_i32 s20, s14, 15
	s_add_i32 s15, s20, 1
	v_cmp_ge_u32_e32 vcc, s20, v52
	v_lshlrev_b32_e32 v16, 16, v188
	v_and_b32_e32 v17, 0xffff0000, v188
	v_lshlrev_b32_e32 v18, 16, v189
	v_and_b32_e32 v19, 0xffff0000, v189
	v_lshlrev_b32_e32 v20, 16, v190
	v_and_b32_e32 v21, 0xffff0000, v190
	v_lshlrev_b32_e32 v22, 16, v191
	v_and_b32_e32 v23, 0xffff0000, v191
	s_and_saveexec_b64 s[26:27], vcc
	v_pk_add_f32 v[32:33], v[32:33], v[16:17] neg_lo:[0,1] neg_hi:[0,1]
	v_pk_add_f32 v[34:35], v[34:35], v[18:19] neg_lo:[0,1] neg_hi:[0,1]
	v_pk_add_f32 v[36:37], v[36:37], v[20:21] neg_lo:[0,1] neg_hi:[0,1]
	v_pk_add_f32 v[38:39], v[38:39], v[22:23] neg_lo:[0,1] neg_hi:[0,1]
	s_or_b64 exec, exec, s[26:27]
	v_min_u32_e32 v40, s15, v52
	v_cvt_f32_ubyte0_e32 v40, v40
	v_div_scale_f32 v41, s[26:27], v40, v40, 1.0
	v_rcp_f32_e32 v42, v41
	v_div_scale_f32 v43, vcc, 1.0, v40, 1.0
	v_fma_f32 v44, -v41, v42, 1.0
	v_fmac_f32_e32 v42, v44, v42
	v_mul_f32_e32 v44, v43, v42
	v_fma_f32 v45, -v41, v44, v43
	v_fmac_f32_e32 v44, v45, v42
	v_fma_f32 v41, -v41, v44, v43
	v_div_fmas_f32 v41, v41, v42, v44
	v_div_fixup_f32 v40, v41, v40, 1.0
	v_fma_f32 v46, v40, v32, -v8
	v_fma_f32 v47, v40, v33, -v9
	v_cvt_pk_bf16_f32 v24, v46, v47
	v_fma_f32 v46, v40, v34, -v10
	v_fma_f32 v47, v40, v35, -v11
	v_cvt_pk_bf16_f32 v25, v46, v47
	v_fma_f32 v46, v40, v36, -v12
	v_fma_f32 v47, v40, v37, -v13
	v_cvt_pk_bf16_f32 v26, v46, v47
	v_fma_f32 v46, v40, v38, -v14
	v_fma_f32 v47, v40, v39, -v15
	v_cvt_pk_bf16_f32 v27, v46, v47
	global_store_dwordx4 v[28:29], v[24:27], off offset:2048
	s_nop 1
	v_add_co_u32_e32 v4, vcc, 0x19000, v58
	s_nop 1
	v_addc_co_u32_e32 v5, vcc, 0, v59, vcc
	v_add_co_u32_e32 v6, vcc, 0x19000, v62
	s_nop 1
	v_addc_co_u32_e32 v7, vcc, 0, v63, vcc
	global_load_dwordx4 v[128:131], v[4:5], off offset:-4096
	global_load_dwordx4 v[132:135], v[6:7], off offset:-4096
	global_load_dwordx4 v[136:139], v[4:5], off
	global_load_dwordx4 v[140:143], v[6:7], off
	v_add_co_u32_e32 v4, vcc, 0x1b000, v58
	s_nop 1
	v_addc_co_u32_e32 v5, vcc, 0, v59, vcc
	v_add_co_u32_e32 v6, vcc, 0x1b000, v62
	s_nop 1
	v_addc_co_u32_e32 v7, vcc, 0, v63, vcc
	global_load_dwordx4 v[144:147], v[4:5], off offset:-4096
	global_load_dwordx4 v[148:151], v[6:7], off offset:-4096
	global_load_dwordx4 v[152:155], v[4:5], off
	global_load_dwordx4 v[156:159], v[6:7], off
	v_add_co_u32_e32 v4, vcc, 0x1d000, v58
	s_nop 1
	v_addc_co_u32_e32 v5, vcc, 0, v59, vcc
	v_add_co_u32_e32 v6, vcc, 0x1d000, v62
	s_nop 1
	v_addc_co_u32_e32 v7, vcc, 0, v63, vcc
	global_load_dwordx4 v[160:163], v[4:5], off offset:-4096
	global_load_dwordx4 v[164:167], v[6:7], off offset:-4096
	global_load_dwordx4 v[168:171], v[4:5], off
	global_load_dwordx4 v[172:175], v[6:7], off
	v_add_co_u32_e32 v4, vcc, 0x1f000, v58
	s_nop 1
	v_addc_co_u32_e32 v5, vcc, 0, v59, vcc
	v_add_co_u32_e32 v6, vcc, 0x1f000, v62
	s_nop 1
	v_addc_co_u32_e32 v7, vcc, 0, v63, vcc
	global_load_dwordx4 v[176:179], v[4:5], off offset:-4096
	global_load_dwordx4 v[180:183], v[6:7], off offset:-4096
	global_load_dwordx4 v[184:187], v[4:5], off
	global_load_dwordx4 v[188:191], v[6:7], off
	s_waitcnt vmcnt(38)
	v_lshlrev_b32_e32 v8, 16, v64
	v_and_b32_e32 v9, 0xffff0000, v64
	v_lshlrev_b32_e32 v10, 16, v65
	v_and_b32_e32 v11, 0xffff0000, v65
	v_lshlrev_b32_e32 v12, 16, v66
	v_and_b32_e32 v13, 0xffff0000, v66
	v_lshlrev_b32_e32 v14, 16, v67
	v_and_b32_e32 v15, 0xffff0000, v67
	v_pk_add_f32 v[32:33], v[32:33], v[8:9]
	v_pk_add_f32 v[34:35], v[34:35], v[10:11]
	v_pk_add_f32 v[36:37], v[36:37], v[12:13]
	v_pk_add_f32 v[38:39], v[38:39], v[14:15]
	s_add_i32 s20, s14, 16
	s_add_i32 s15, s20, 1
	v_cmp_ge_u32_e32 vcc, s20, v52
	v_lshlrev_b32_e32 v16, 16, v68
	v_and_b32_e32 v17, 0xffff0000, v68
	v_lshlrev_b32_e32 v18, 16, v69
	v_and_b32_e32 v19, 0xffff0000, v69
	v_lshlrev_b32_e32 v20, 16, v70
	v_and_b32_e32 v21, 0xffff0000, v70
	v_lshlrev_b32_e32 v22, 16, v71
	v_and_b32_e32 v23, 0xffff0000, v71
	s_and_saveexec_b64 s[26:27], vcc
	v_pk_add_f32 v[32:33], v[32:33], v[16:17] neg_lo:[0,1] neg_hi:[0,1]
	v_pk_add_f32 v[34:35], v[34:35], v[18:19] neg_lo:[0,1] neg_hi:[0,1]
	v_pk_add_f32 v[36:37], v[36:37], v[20:21] neg_lo:[0,1] neg_hi:[0,1]
	v_pk_add_f32 v[38:39], v[38:39], v[22:23] neg_lo:[0,1] neg_hi:[0,1]
	s_or_b64 exec, exec, s[26:27]
	v_min_u32_e32 v40, s15, v52
	v_cvt_f32_ubyte0_e32 v40, v40
	v_div_scale_f32 v41, s[26:27], v40, v40, 1.0
	v_rcp_f32_e32 v42, v41
	v_div_scale_f32 v43, vcc, 1.0, v40, 1.0
	v_fma_f32 v44, -v41, v42, 1.0
	v_fmac_f32_e32 v42, v44, v42
	v_mul_f32_e32 v44, v43, v42
	v_fma_f32 v45, -v41, v44, v43
	v_fmac_f32_e32 v44, v45, v42
	v_fma_f32 v41, -v41, v44, v43
	v_div_fmas_f32 v41, v41, v42, v44
	v_div_fixup_f32 v40, v41, v40, 1.0
	v_fma_f32 v46, v40, v32, -v8
	v_fma_f32 v47, v40, v33, -v9
	v_cvt_pk_bf16_f32 v24, v46, v47
	v_fma_f32 v46, v40, v34, -v10
	v_fma_f32 v47, v40, v35, -v11
	v_cvt_pk_bf16_f32 v25, v46, v47
	v_fma_f32 v46, v40, v36, -v12
	v_fma_f32 v47, v40, v37, -v13
	v_cvt_pk_bf16_f32 v26, v46, v47
	v_fma_f32 v46, v40, v38, -v14
	v_fma_f32 v47, v40, v39, -v15
	v_cvt_pk_bf16_f32 v27, v46, v47
	v_add_co_u32_e32 v28, vcc, 0x8000, v56
	s_nop 1
	v_addc_co_u32_e32 v29, vcc, 0, v57, vcc
	global_store_dwordx4 v[28:29], v[24:27], off
	s_waitcnt vmcnt(37)
; __device__ __forceinline__ float bf_lo(unsigned w) { return __uint_as_float(w << 16); }
; __device__ __forceinline__ float bf_hi(unsigned w) { return __uint_as_float(w & 0xffff0000u); }
; __device__ __forceinline__ unsigned pk2(float lo, float hi) { return pg8::cvt_pk_bf16(lo, hi); }
; __global__ void __launch_bounds__(NWAVES * 64, 2) trunk_fwd(Args args) {
;     ...
;                 for (int i0 = 0; i0 < 32; i0 += 4) {
;                     v4u qq[4], oo[4];
; #pragma unroll
;                     for (int k = 0; k < 4; ++k) { qq[k] = *(const v4u*)(up + (size_t)(i0 + k) * 2048); oo[k] = *(const v4u*)(up + ((long)(i0 + k) - w) * 2048); }
; #pragma unroll
;                     for (int k = 0; k < 4; ++k) { const int i = i0 + k; const v4u q = qq[k], o = oo[k];
;                     float cur[8] = {bf_lo(q.x), bf_hi(q.x), bf_lo(q.y), bf_hi(q.y), bf_lo(q.z), bf_hi(q.z), bf_lo(q.w), bf_hi(q.w)};
; #pragma unroll
;                     for (int e = 0; e < 8; ++e) sum[e] += cur[e];
;                     const int t = t0 + i;
;                     if (t - w >= 0) {
;                         sum[0] -= bf_lo(o.x); sum[1] -= bf_hi(o.x); sum[2] -= bf_lo(o.y); sum[3] -= bf_hi(o.y); sum[4] -= bf_lo(o.z); sum[5] -= bf_hi(o.z); sum[6] -= bf_lo(o.w); sum[7] -= bf_hi(o.w); }
;                     const float rc = 1.0f / (float)((t + 1) < w ? (t + 1) : w);
;                     v4u r; r.x = pk2(sum[0] * rc - cur[0], sum[1] * rc - cur[1]); r.y = pk2(sum[2] * rc - cur[2], sum[3] * rc - cur[3]); r.z = pk2(sum[4] * rc - cur[4], sum[5] * rc - cur[5]); r.w = pk2(sum[6] * rc - cur[6], sum[7] * rc - cur[7]);
;                     *(v4u*)(op + (size_t)i * 1024) = r; }
	v_lshlrev_b32_e32 v8, 16, v72
	v_and_b32_e32 v9, 0xffff0000, v72
	v_lshlrev_b32_e32 v10, 16, v73
	v_and_b32_e32 v11, 0xffff0000, v73
	v_lshlrev_b32_e32 v12, 16, v74
	v_and_b32_e32 v13, 0xffff0000, v74
	v_lshlrev_b32_e32 v14, 16, v75
	v_and_b32_e32 v15, 0xffff0000, v75
	v_pk_add_f32 v[32:33], v[32:33], v[8:9]
	v_pk_add_f32 v[34:35], v[34:35], v[10:11]
	v_pk_add_f32 v[36:37], v[36:37], v[12:13]
	v_pk_add_f32 v[38:39], v[38:39], v[14:15]
	s_add_i32 s20, s14, 17
	s_add_i32 s15, s20, 1
	v_cmp_ge_u32_e32 vcc, s20, v52
	v_lshlrev_b32_e32 v16, 16, v76
	v_and_b32_e32 v17, 0xffff0000, v76
	v_lshlrev_b32_e32 v18, 16, v77
	v_and_b32_e32 v19, 0xffff0000, v77
	v_lshlrev_b32_e32 v20, 16, v78
	v_and_b32_e32 v21, 0xffff0000, v78
	v_lshlrev_b32_e32 v22, 16, v79
	v_and_b32_e32 v23, 0xffff0000, v79
	s_and_saveexec_b64 s[26:27], vcc
	v_pk_add_f32 v[32:33], v[32:33], v[16:17] neg_lo:[0,1] neg_hi:[0,1]
	v_pk_add_f32 v[34:35], v[34:35], v[18:19] neg_lo:[0,1] neg_hi:[0,1]
	v_pk_add_f32 v[36:37], v[36:37], v[20:21] neg_lo:[0,1] neg_hi:[0,1]
	v_pk_add_f32 v[38:39], v[38:39], v[22:23] neg_lo:[0,1] neg_hi:[0,1]
	s_or_b64 exec, exec, s[26:27]
	v_min_u32_e32 v40, s15, v52
	v_cvt_f32_ubyte0_e32 v40, v40
	v_div_scale_f32 v41, s[26:27], v40, v40, 1.0
	v_rcp_f32_e32 v42, v41
	v_div_scale_f32 v43, vcc, 1.0, v40, 1.0
	v_fma_f32 v44, -v41, v42, 1.0
	v_fmac_f32_e32 v42, v44, v42
	v_mul_f32_e32 v44, v43, v42
	v_fma_f32 v45, -v41, v44, v43
	v_fmac_f32_e32 v44, v45, v42
	v_fma_f32 v41, -v41, v44, v43
	v_div_fmas_f32 v41, v41, v42, v44
	v_div_fixup_f32 v40, v41, v40, 1.0
	v_fma_f32 v46, v40, v32, -v8
	v_fma_f32 v47, v40, v33, -v9
	v_cvt_pk_bf16_f32 v24, v46, v47
	v_fma_f32 v46, v40, v34, -v10
	v_fma_f32 v47, v40, v35, -v11
	v_cvt_pk_bf16_f32 v25, v46, v47
	v_fma_f32 v46, v40, v36, -v12
	v_fma_f32 v47, v40, v37, -v13
	v_cvt_pk_bf16_f32 v26, v46, v47
	v_fma_f32 v46, v40, v38, -v14
	v_fma_f32 v47, v40, v39, -v15
	v_cvt_pk_bf16_f32 v27, v46, v47
	global_store_dwordx4 v[28:29], v[24:27], off offset:2048
	s_nop 1
	s_waitcnt vmcnt(36)
	v_lshlrev_b32_e32 v8, 16, v80
	v_and_b32_e32 v9, 0xffff0000, v80
	v_lshlrev_b32_e32 v10, 16, v81
	v_and_b32_e32 v11, 0xffff0000, v81
	v_lshlrev_b32_e32 v12, 16, v82
	v_and_b32_e32 v13, 0xffff0000, v82
	v_lshlrev_b32_e32 v14, 16, v83
	v_and_b32_e32 v15, 0xffff0000, v83
	v_pk_add_f32 v[32:33], v[32:33], v[8:9]
	v_pk_add_f32 v[34:35], v[34:35], v[10:11]
	v_pk_add_f32 v[36:37], v[36:37], v[12:13]
	v_pk_add_f32 v[38:39], v[38:39], v[14:15]
	s_add_i32 s20, s14, 18
	s_add_i32 s15, s20, 1
	v_cmp_ge_u32_e32 vcc, s20, v52
	v_lshlrev_b32_e32 v16, 16, v84
	v_and_b32_e32 v17, 0xffff0000, v84
	v_lshlrev_b32_e32 v18, 16, v85
	v_and_b32_e32 v19, 0xffff0000, v85
	v_lshlrev_b32_e32 v20, 16, v86
	v_and_b32_e32 v21, 0xffff0000, v86
	v_lshlrev_b32_e32 v22, 16, v87
	v_and_b32_e32 v23, 0xffff0000, v87
	s_and_saveexec_b64 s[26:27], vcc
	v_pk_add_f32 v[32:33], v[32:33], v[16:17] neg_lo:[0,1] neg_hi:[0,1]
	v_pk_add_f32 v[34:35], v[34:35], v[18:19] neg_lo:[0,1] neg_hi:[0,1]
	v_pk_add_f32 v[36:37], v[36:37], v[20:21] neg_lo:[0,1] neg_hi:[0,1]
	v_pk_add_f32 v[38:39], v[38:39], v[22:23] neg_lo:[0,1] neg_hi:[0,1]
	s_or_b64 exec, exec, s[26:27]
	v_min_u32_e32 v40, s15, v52
	v_cvt_f32_ubyte0_e32 v40, v40
	v_div_scale_f32 v41, s[26:27], v40, v40, 1.0
	v_rcp_f32_e32 v42, v41
	v_div_scale_f32 v43, vcc, 1.0, v40, 1.0
	v_fma_f32 v44, -v41, v42, 1.0
	v_fmac_f32_e32 v42, v44, v42
	v_mul_f32_e32 v44, v43, v42
	v_fma_f32 v45, -v41, v44, v43
	v_fmac_f32_e32 v44, v45, v42
	v_fma_f32 v41, -v41, v44, v43
	v_div_fmas_f32 v41, v41, v42, v44
	v_div_fixup_f32 v40, v41, v40, 1.0
	v_fma_f32 v46, v40, v32, -v8
	v_fma_f32 v47, v40, v33, -v9
	v_cvt_pk_bf16_f32 v24, v46, v47
	v_fma_f32 v46, v40, v34, -v10
	v_fma_f32 v47, v40, v35, -v11
	v_cvt_pk_bf16_f32 v25, v46, v47
	v_fma_f32 v46, v40, v36, -v12
	v_fma_f32 v47, v40, v37, -v13
	v_cvt_pk_bf16_f32 v26, v46, v47
	v_fma_f32 v46, v40, v38, -v14
	v_fma_f32 v47, v40, v39, -v15
	v_cvt_pk_bf16_f32 v27, v46, v47
	v_add_co_u32_e32 v28, vcc, 0x9000, v56
	s_nop 1
	v_addc_co_u32_e32 v29, vcc, 0, v57, vcc
	global_store_dwordx4 v[28:29], v[24:27], off
	s_waitcnt vmcnt(35)
	v_lshlrev_b32_e32 v8, 16, v88
	v_and_b32_e32 v9, 0xffff0000, v88
	v_lshlrev_b32_e32 v10, 16, v89
	v_and_b32_e32 v11, 0xffff0000, v89
	v_lshlrev_b32_e32 v12, 16, v90
	v_and_b32_e32 v13, 0xffff0000, v90
	v_lshlrev_b32_e32 v14, 16, v91
	v_and_b32_e32 v15, 0xffff0000, v91
	v_pk_add_f32 v[32:33], v[32:33], v[8:9]
	v_pk_add_f32 v[34:35], v[34:35], v[10:11]
	v_pk_add_f32 v[36:37], v[36:37], v[12:13]
	v_pk_add_f32 v[38:39], v[38:39], v[14:15]
	s_add_i32 s20, s14, 19
	s_add_i32 s15, s20, 1
	v_cmp_ge_u32_e32 vcc, s20, v52
	v_lshlrev_b32_e32 v16, 16, v92
	v_and_b32_e32 v17, 0xffff0000, v92
	v_lshlrev_b32_e32 v18, 16, v93
	v_and_b32_e32 v19, 0xffff0000, v93
	v_lshlrev_b32_e32 v20, 16, v94
	v_and_b32_e32 v21, 0xffff0000, v94
	v_lshlrev_b32_e32 v22, 16, v95
	v_and_b32_e32 v23, 0xffff0000, v95
	s_and_saveexec_b64 s[26:27], vcc
	v_pk_add_f32 v[32:33], v[32:33], v[16:17] neg_lo:[0,1] neg_hi:[0,1]
	v_pk_add_f32 v[34:35], v[34:35], v[18:19] neg_lo:[0,1] neg_hi:[0,1]
	v_pk_add_f32 v[36:37], v[36:37], v[20:21] neg_lo:[0,1] neg_hi:[0,1]
	v_pk_add_f32 v[38:39], v[38:39], v[22:23] neg_lo:[0,1] neg_hi:[0,1]
	s_or_b64 exec, exec, s[26:27]
	v_min_u32_e32 v40, s15, v52
	v_cvt_f32_ubyte0_e32 v40, v40
	v_div_scale_f32 v41, s[26:27], v40, v40, 1.0
	v_rcp_f32_e32 v42, v41
	v_div_scale_f32 v43, vcc, 1.0, v40, 1.0
	v_fma_f32 v44, -v41, v42, 1.0
	v_fmac_f32_e32 v42, v44, v42
	v_mul_f32_e32 v44, v43, v42
	v_fma_f32 v45, -v41, v44, v43
	v_fmac_f32_e32 v44, v45, v42
	v_fma_f32 v41, -v41, v44, v43
	v_div_fmas_f32 v41, v41, v42, v44
	v_div_fixup_f32 v40, v41, v40, 1.0
	v_fma_f32 v46, v40, v32, -v8
	v_fma_f32 v47, v40, v33, -v9
	v_cvt_pk_bf16_f32 v24, v46, v47
	v_fma_f32 v46, v40, v34, -v10
	v_fma_f32 v47, v40, v35, -v11
	v_cvt_pk_bf16_f32 v25, v46, v47
	v_fma_f32 v46, v40, v36, -v12
	v_fma_f32 v47, v40, v37, -v13
	v_cvt_pk_bf16_f32 v26, v46, v47
	v_fma_f32 v46, v40, v38, -v14
	v_fma_f32 v47, v40, v39, -v15
	v_cvt_pk_bf16_f32 v27, v46, v47
	global_store_dwordx4 v[28:29], v[24:27], off offset:2048
	s_nop 1
	s_waitcnt vmcnt(34)
; __device__ __forceinline__ float bf_lo(unsigned w) { return __uint_as_float(w << 16); }
; __device__ __forceinline__ float bf_hi(unsigned w) { return __uint_as_float(w & 0xffff0000u); }
; __device__ __forceinline__ unsigned pk2(float lo, float hi) { return pg8::cvt_pk_bf16(lo, hi); }
; __global__ void __launch_bounds__(NWAVES * 64, 2) trunk_fwd(Args args) {
;     ...
;                 for (int i0 = 0; i0 < 32; i0 += 4) {
;                     v4u qq[4], oo[4];
; #pragma unroll
;                     for (int k = 0; k < 4; ++k) { qq[k] = *(const v4u*)(up + (size_t)(i0 + k) * 2048); oo[k] = *(const v4u*)(up + ((long)(i0 + k) - w) * 2048); }
; #pragma unroll
;                     for (int k = 0; k < 4; ++k) { const int i = i0 + k; const v4u q = qq[k], o = oo[k];
;                     float cur[8] = {bf_lo(q.x), bf_hi(q.x), bf_lo(q.y), bf_hi(q.y), bf_lo(q.z), bf_hi(q.z), bf_lo(q.w), bf_hi(q.w)};
; #pragma unroll
;                     for (int e = 0; e < 8; ++e) sum[e] += cur[e];
;                     const int t = t0 + i;
;                     if (t - w >= 0) {
;                         sum[0] -= bf_lo(o.x); sum[1] -= bf_hi(o.x); sum[2] -= bf_lo(o.y); sum[3] -= bf_hi(o.y); sum[4] -= bf_lo(o.z); sum[5] -= bf_hi(o.z); sum[6] -= bf_lo(o.w); sum[7] -= bf_hi(o.w); }
;                     const float rc = 1.0f / (float)((t + 1) < w ? (t + 1) : w);
;                     v4u r; r.x = pk2(sum[0] * rc - cur[0], sum[1] * rc - cur[1]); r.y = pk2(sum[2] * rc - cur[2], sum[3] * rc - cur[3]); r.z = pk2(sum[4] * rc - cur[4], sum[5] * rc - cur[5]); r.w = pk2(sum[6] * rc - cur[6], sum[7] * rc - cur[7]);
;                     *(v4u*)(op + (size_t)i * 1024) = r; }
	v_lshlrev_b32_e32 v8, 16, v96
	v_and_b32_e32 v9, 0xffff0000, v96
	v_lshlrev_b32_e32 v10, 16, v97
	v_and_b32_e32 v11, 0xffff0000, v97
	v_lshlrev_b32_e32 v12, 16, v98
	v_and_b32_e32 v13, 0xffff0000, v98
	v_lshlrev_b32_e32 v14, 16, v99
	v_and_b32_e32 v15, 0xffff0000, v99
	v_pk_add_f32 v[32:33], v[32:33], v[8:9]
	v_pk_add_f32 v[34:35], v[34:35], v[10:11]
	v_pk_add_f32 v[36:37], v[36:37], v[12:13]
	v_pk_add_f32 v[38:39], v[38:39], v[14:15]
	s_add_i32 s20, s14, 20
	s_add_i32 s15, s20, 1
	v_cmp_ge_u32_e32 vcc, s20, v52
	v_lshlrev_b32_e32 v16, 16, v100
	v_and_b32_e32 v17, 0xffff0000, v100
	v_lshlrev_b32_e32 v18, 16, v101
	v_and_b32_e32 v19, 0xffff0000, v101
	v_lshlrev_b32_e32 v20, 16, v102
	v_and_b32_e32 v21, 0xffff0000, v102
	v_lshlrev_b32_e32 v22, 16, v103
	v_and_b32_e32 v23, 0xffff0000, v103
	s_and_saveexec_b64 s[26:27], vcc
	v_pk_add_f32 v[32:33], v[32:33], v[16:17] neg_lo:[0,1] neg_hi:[0,1]
	v_pk_add_f32 v[34:35], v[34:35], v[18:19] neg_lo:[0,1] neg_hi:[0,1]
	v_pk_add_f32 v[36:37], v[36:37], v[20:21] neg_lo:[0,1] neg_hi:[0,1]
	v_pk_add_f32 v[38:39], v[38:39], v[22:23] neg_lo:[0,1] neg_hi:[0,1]
	s_or_b64 exec, exec, s[26:27]
	v_min_u32_e32 v40, s15, v52
	v_cvt_f32_ubyte0_e32 v40, v40
	v_div_scale_f32 v41, s[26:27], v40, v40, 1.0
	v_rcp_f32_e32 v42, v41
	v_div_scale_f32 v43, vcc, 1.0, v40, 1.0
	v_fma_f32 v44, -v41, v42, 1.0
	v_fmac_f32_e32 v42, v44, v42
	v_mul_f32_e32 v44, v43, v42
	v_fma_f32 v45, -v41, v44, v43
	v_fmac_f32_e32 v44, v45, v42
	v_fma_f32 v41, -v41, v44, v43
	v_div_fmas_f32 v41, v41, v42, v44
	v_div_fixup_f32 v40, v41, v40, 1.0
	v_fma_f32 v46, v40, v32, -v8
	v_fma_f32 v47, v40, v33, -v9
	v_cvt_pk_bf16_f32 v24, v46, v47
	v_fma_f32 v46, v40, v34, -v10
	v_fma_f32 v47, v40, v35, -v11
	v_cvt_pk_bf16_f32 v25, v46, v47
	v_fma_f32 v46, v40, v36, -v12
	v_fma_f32 v47, v40, v37, -v13
	v_cvt_pk_bf16_f32 v26, v46, v47
	v_fma_f32 v46, v40, v38, -v14
	v_fma_f32 v47, v40, v39, -v15
	v_cvt_pk_bf16_f32 v27, v46, v47
	v_add_co_u32_e32 v28, vcc, 0xa000, v56
	s_nop 1
	v_addc_co_u32_e32 v29, vcc, 0, v57, vcc
	global_store_dwordx4 v[28:29], v[24:27], off
	s_waitcnt vmcnt(33)
	v_lshlrev_b32_e32 v8, 16, v104
	v_and_b32_e32 v9, 0xffff0000, v104
	v_lshlrev_b32_e32 v10, 16, v105
	v_and_b32_e32 v11, 0xffff0000, v105
	v_lshlrev_b32_e32 v12, 16, v106
	v_and_b32_e32 v13, 0xffff0000, v106
	v_lshlrev_b32_e32 v14, 16, v107
	v_and_b32_e32 v15, 0xffff0000, v107
	v_pk_add_f32 v[32:33], v[32:33], v[8:9]
	v_pk_add_f32 v[34:35], v[34:35], v[10:11]
	v_pk_add_f32 v[36:37], v[36:37], v[12:13]
	v_pk_add_f32 v[38:39], v[38:39], v[14:15]
	s_add_i32 s20, s14, 21
	s_add_i32 s15, s20, 1
	v_cmp_ge_u32_e32 vcc, s20, v52
	v_lshlrev_b32_e32 v16, 16, v108
	v_and_b32_e32 v17, 0xffff0000, v108
	v_lshlrev_b32_e32 v18, 16, v109
	v_and_b32_e32 v19, 0xffff0000, v109
	v_lshlrev_b32_e32 v20, 16, v110
	v_and_b32_e32 v21, 0xffff0000, v110
	v_lshlrev_b32_e32 v22, 16, v111
	v_and_b32_e32 v23, 0xffff0000, v111
	s_and_saveexec_b64 s[26:27], vcc
	v_pk_add_f32 v[32:33], v[32:33], v[16:17] neg_lo:[0,1] neg_hi:[0,1]
	v_pk_add_f32 v[34:35], v[34:35], v[18:19] neg_lo:[0,1] neg_hi:[0,1]
	v_pk_add_f32 v[36:37], v[36:37], v[20:21] neg_lo:[0,1] neg_hi:[0,1]
	v_pk_add_f32 v[38:39], v[38:39], v[22:23] neg_lo:[0,1] neg_hi:[0,1]
	s_or_b64 exec, exec, s[26:27]
	v_min_u32_e32 v40, s15, v52
	v_cvt_f32_ubyte0_e32 v40, v40
	v_div_scale_f32 v41, s[26:27], v40, v40, 1.0
	v_rcp_f32_e32 v42, v41
	v_div_scale_f32 v43, vcc, 1.0, v40, 1.0
	v_fma_f32 v44, -v41, v42, 1.0
	v_fmac_f32_e32 v42, v44, v42
	v_mul_f32_e32 v44, v43, v42
	v_fma_f32 v45, -v41, v44, v43
	v_fmac_f32_e32 v44, v45, v42
	v_fma_f32 v41, -v41, v44, v43
	v_div_fmas_f32 v41, v41, v42, v44
	v_div_fixup_f32 v40, v41, v40, 1.0
	v_fma_f32 v46, v40, v32, -v8
	v_fma_f32 v47, v40, v33, -v9
	v_cvt_pk_bf16_f32 v24, v46, v47
	v_fma_f32 v46, v40, v34, -v10
	v_fma_f32 v47, v40, v35, -v11
	v_cvt_pk_bf16_f32 v25, v46, v47
	v_fma_f32 v46, v40, v36, -v12
	v_fma_f32 v47, v40, v37, -v13
	v_cvt_pk_bf16_f32 v26, v46, v47
	v_fma_f32 v46, v40, v38, -v14
	v_fma_f32 v47, v40, v39, -v15
	v_cvt_pk_bf16_f32 v27, v46, v47
	global_store_dwordx4 v[28:29], v[24:27], off offset:2048
	s_nop 1
	s_waitcnt vmcnt(32)
	v_lshlrev_b32_e32 v8, 16, v112
	v_and_b32_e32 v9, 0xffff0000, v112
	v_lshlrev_b32_e32 v10, 16, v113
	v_and_b32_e32 v11, 0xffff0000, v113
	v_lshlrev_b32_e32 v12, 16, v114
	v_and_b32_e32 v13, 0xffff0000, v114
	v_lshlrev_b32_e32 v14, 16, v115
	v_and_b32_e32 v15, 0xffff0000, v115
	v_pk_add_f32 v[32:33], v[32:33], v[8:9]
	v_pk_add_f32 v[34:35], v[34:35], v[10:11]
	v_pk_add_f32 v[36:37], v[36:37], v[12:13]
	v_pk_add_f32 v[38:39], v[38:39], v[14:15]
	s_add_i32 s20, s14, 22
	s_add_i32 s15, s20, 1
	v_cmp_ge_u32_e32 vcc, s20, v52
	v_lshlrev_b32_e32 v16, 16, v116
	v_and_b32_e32 v17, 0xffff0000, v116
	v_lshlrev_b32_e32 v18, 16, v117
	v_and_b32_e32 v19, 0xffff0000, v117
	v_lshlrev_b32_e32 v20, 16, v118
	v_and_b32_e32 v21, 0xffff0000, v118
	v_lshlrev_b32_e32 v22, 16, v119
	v_and_b32_e32 v23, 0xffff0000, v119
	s_and_saveexec_b64 s[26:27], vcc
	v_pk_add_f32 v[32:33], v[32:33], v[16:17] neg_lo:[0,1] neg_hi:[0,1]
	v_pk_add_f32 v[34:35], v[34:35], v[18:19] neg_lo:[0,1] neg_hi:[0,1]
	v_pk_add_f32 v[36:37], v[36:37], v[20:21] neg_lo:[0,1] neg_hi:[0,1]
	v_pk_add_f32 v[38:39], v[38:39], v[22:23] neg_lo:[0,1] neg_hi:[0,1]
	s_or_b64 exec, exec, s[26:27]
	v_min_u32_e32 v40, s15, v52
	v_cvt_f32_ubyte0_e32 v40, v40
	v_div_scale_f32 v41, s[26:27], v40, v40, 1.0
	v_rcp_f32_e32 v42, v41
	v_div_scale_f32 v43, vcc, 1.0, v40, 1.0
	v_fma_f32 v44, -v41, v42, 1.0
	v_fmac_f32_e32 v42, v44, v42
	v_mul_f32_e32 v44, v43, v42
	v_fma_f32 v45, -v41, v44, v43
	v_fmac_f32_e32 v44, v45, v42
	v_fma_f32 v41, -v41, v44, v43
	v_div_fmas_f32 v41, v41, v42, v44
	v_div_fixup_f32 v40, v41, v40, 1.0
	v_fma_f32 v46, v40, v32, -v8
	v_fma_f32 v47, v40, v33, -v9
	v_cvt_pk_bf16_f32 v24, v46, v47
	v_fma_f32 v46, v40, v34, -v10
	v_fma_f32 v47, v40, v35, -v11
	v_cvt_pk_bf16_f32 v25, v46, v47
	v_fma_f32 v46, v40, v36, -v12
	v_fma_f32 v47, v40, v37, -v13
	v_cvt_pk_bf16_f32 v26, v46, v47
	v_fma_f32 v46, v40, v38, -v14
	v_fma_f32 v47, v40, v39, -v15
	v_cvt_pk_bf16_f32 v27, v46, v47
	v_add_co_u32_e32 v28, vcc, 0xb000, v56
	s_nop 1
	v_addc_co_u32_e32 v29, vcc, 0, v57, vcc
	global_store_dwordx4 v[28:29], v[24:27], off
	s_waitcnt vmcnt(31)
; __device__ __forceinline__ float bf_lo(unsigned w) { return __uint_as_float(w << 16); }
; __device__ __forceinline__ float bf_hi(unsigned w) { return __uint_as_float(w & 0xffff0000u); }
; __device__ __forceinline__ unsigned pk2(float lo, float hi) { return pg8::cvt_pk_bf16(lo, hi); }
; __global__ void __launch_bounds__(NWAVES * 64, 2) trunk_fwd(Args args) {
;     ...
;                 for (int i0 = 0; i0 < 32; i0 += 4) {
;                     v4u qq[4], oo[4];
; #pragma unroll
;                     for (int k = 0; k < 4; ++k) { qq[k] = *(const v4u*)(up + (size_t)(i0 + k) * 2048); oo[k] = *(const v4u*)(up + ((long)(i0 + k) - w) * 2048); }
; #pragma unroll
;                     for (int k = 0; k < 4; ++k) { const int i = i0 + k; const v4u q = qq[k], o = oo[k];
;                     float cur[8] = {bf_lo(q.x), bf_hi(q.x), bf_lo(q.y), bf_hi(q.y), bf_lo(q.z), bf_hi(q.z), bf_lo(q.w), bf_hi(q.w)};
; #pragma unroll
;                     for (int e = 0; e < 8; ++e) sum[e] += cur[e];
;                     const int t = t0 + i;
;                     if (t - w >= 0) {
;                         sum[0] -= bf_lo(o.x); sum[1] -= bf_hi(o.x); sum[2] -= bf_lo(o.y); sum[3] -= bf_hi(o.y); sum[4] -= bf_lo(o.z); sum[5] -= bf_hi(o.z); sum[6] -= bf_lo(o.w); sum[7] -= bf_hi(o.w); }
;                     const float rc = 1.0f / (float)((t + 1) < w ? (t + 1) : w);
;                     v4u r; r.x = pk2(sum[0] * rc - cur[0], sum[1] * rc - cur[1]); r.y = pk2(sum[2] * rc - cur[2], sum[3] * rc - cur[3]); r.z = pk2(sum[4] * rc - cur[4], sum[5] * rc - cur[5]); r.w = pk2(sum[6] * rc - cur[6], sum[7] * rc - cur[7]);
;                     *(v4u*)(op + (size_t)i * 1024) = r; }
	v_lshlrev_b32_e32 v8, 16, v120
	v_and_b32_e32 v9, 0xffff0000, v120
	v_lshlrev_b32_e32 v10, 16, v121
	v_and_b32_e32 v11, 0xffff0000, v121
	v_lshlrev_b32_e32 v12, 16, v122
	v_and_b32_e32 v13, 0xffff0000, v122
	v_lshlrev_b32_e32 v14, 16, v123
	v_and_b32_e32 v15, 0xffff0000, v123
	v_pk_add_f32 v[32:33], v[32:33], v[8:9]
	v_pk_add_f32 v[34:35], v[34:35], v[10:11]
	v_pk_add_f32 v[36:37], v[36:37], v[12:13]
	v_pk_add_f32 v[38:39], v[38:39], v[14:15]
	s_add_i32 s20, s14, 23
	s_add_i32 s15, s20, 1
	v_cmp_ge_u32_e32 vcc, s20, v52
	v_lshlrev_b32_e32 v16, 16, v124
	v_and_b32_e32 v17, 0xffff0000, v124
	v_lshlrev_b32_e32 v18, 16, v125
	v_and_b32_e32 v19, 0xffff0000, v125
	v_lshlrev_b32_e32 v20, 16, v126
	v_and_b32_e32 v21, 0xffff0000, v126
	v_lshlrev_b32_e32 v22, 16, v127
	v_and_b32_e32 v23, 0xffff0000, v127
	s_and_saveexec_b64 s[26:27], vcc
	v_pk_add_f32 v[32:33], v[32:33], v[16:17] neg_lo:[0,1] neg_hi:[0,1]
	v_pk_add_f32 v[34:35], v[34:35], v[18:19] neg_lo:[0,1] neg_hi:[0,1]
	v_pk_add_f32 v[36:37], v[36:37], v[20:21] neg_lo:[0,1] neg_hi:[0,1]
	v_pk_add_f32 v[38:39], v[38:39], v[22:23] neg_lo:[0,1] neg_hi:[0,1]
	s_or_b64 exec, exec, s[26:27]
	v_min_u32_e32 v40, s15, v52
	v_cvt_f32_ubyte0_e32 v40, v40
	v_div_scale_f32 v41, s[26:27], v40, v40, 1.0
	v_rcp_f32_e32 v42, v41
	v_div_scale_f32 v43, vcc, 1.0, v40, 1.0
	v_fma_f32 v44, -v41, v42, 1.0
	v_fmac_f32_e32 v42, v44, v42
	v_mul_f32_e32 v44, v43, v42
	v_fma_f32 v45, -v41, v44, v43
	v_fmac_f32_e32 v44, v45, v42
	v_fma_f32 v41, -v41, v44, v43
	v_div_fmas_f32 v41, v41, v42, v44
	v_div_fixup_f32 v40, v41, v40, 1.0
	v_fma_f32 v46, v40, v32, -v8
	v_fma_f32 v47, v40, v33, -v9
	v_cvt_pk_bf16_f32 v24, v46, v47
	v_fma_f32 v46, v40, v34, -v10
	v_fma_f32 v47, v40, v35, -v11
	v_cvt_pk_bf16_f32 v25, v46, v47
	v_fma_f32 v46, v40, v36, -v12
	v_fma_f32 v47, v40, v37, -v13
	v_cvt_pk_bf16_f32 v26, v46, v47
	v_fma_f32 v46, v40, v38, -v14
	v_fma_f32 v47, v40, v39, -v15
	v_cvt_pk_bf16_f32 v27, v46, v47
	global_store_dwordx4 v[28:29], v[24:27], off offset:2048
	s_nop 1
	s_waitcnt vmcnt(22)
	v_lshlrev_b32_e32 v8, 16, v128
	v_and_b32_e32 v9, 0xffff0000, v128
	v_lshlrev_b32_e32 v10, 16, v129
	v_and_b32_e32 v11, 0xffff0000, v129
	v_lshlrev_b32_e32 v12, 16, v130
	v_and_b32_e32 v13, 0xffff0000, v130
	v_lshlrev_b32_e32 v14, 16, v131
	v_and_b32_e32 v15, 0xffff0000, v131
	v_pk_add_f32 v[32:33], v[32:33], v[8:9]
	v_pk_add_f32 v[34:35], v[34:35], v[10:11]
	v_pk_add_f32 v[36:37], v[36:37], v[12:13]
	v_pk_add_f32 v[38:39], v[38:39], v[14:15]
	s_add_i32 s20, s14, 24
	s_add_i32 s15, s20, 1
	v_cmp_ge_u32_e32 vcc, s20, v52
	v_lshlrev_b32_e32 v16, 16, v132
	v_and_b32_e32 v17, 0xffff0000, v132
	v_lshlrev_b32_e32 v18, 16, v133
	v_and_b32_e32 v19, 0xffff0000, v133
	v_lshlrev_b32_e32 v20, 16, v134
	v_and_b32_e32 v21, 0xffff0000, v134
	v_lshlrev_b32_e32 v22, 16, v135
	v_and_b32_e32 v23, 0xffff0000, v135
	s_and_saveexec_b64 s[26:27], vcc
	v_pk_add_f32 v[32:33], v[32:33], v[16:17] neg_lo:[0,1] neg_hi:[0,1]
	v_pk_add_f32 v[34:35], v[34:35], v[18:19] neg_lo:[0,1] neg_hi:[0,1]
	v_pk_add_f32 v[36:37], v[36:37], v[20:21] neg_lo:[0,1] neg_hi:[0,1]
	v_pk_add_f32 v[38:39], v[38:39], v[22:23] neg_lo:[0,1] neg_hi:[0,1]
	s_or_b64 exec, exec, s[26:27]
	v_min_u32_e32 v40, s15, v52
	v_cvt_f32_ubyte0_e32 v40, v40
	v_div_scale_f32 v41, s[26:27], v40, v40, 1.0
	v_rcp_f32_e32 v42, v41
	v_div_scale_f32 v43, vcc, 1.0, v40, 1.0
	v_fma_f32 v44, -v41, v42, 1.0
	v_fmac_f32_e32 v42, v44, v42
	v_mul_f32_e32 v44, v43, v42
	v_fma_f32 v45, -v41, v44, v43
	v_fmac_f32_e32 v44, v45, v42
	v_fma_f32 v41, -v41, v44, v43
	v_div_fmas_f32 v41, v41, v42, v44
	v_div_fixup_f32 v40, v41, v40, 1.0
	v_fma_f32 v46, v40, v32, -v8
	v_fma_f32 v47, v40, v33, -v9
	v_cvt_pk_bf16_f32 v24, v46, v47
	v_fma_f32 v46, v40, v34, -v10
	v_fma_f32 v47, v40, v35, -v11
	v_cvt_pk_bf16_f32 v25, v46, v47
	v_fma_f32 v46, v40, v36, -v12
	v_fma_f32 v47, v40, v37, -v13
	v_cvt_pk_bf16_f32 v26, v46, v47
	v_fma_f32 v46, v40, v38, -v14
	v_fma_f32 v47, v40, v39, -v15
	v_cvt_pk_bf16_f32 v27, v46, v47
	v_add_co_u32_e32 v28, vcc, 0xc000, v56
	s_nop 1
	v_addc_co_u32_e32 v29, vcc, 0, v57, vcc
	global_store_dwordx4 v[28:29], v[24:27], off
	s_waitcnt vmcnt(21)
	v_lshlrev_b32_e32 v8, 16, v136
	v_and_b32_e32 v9, 0xffff0000, v136
	v_lshlrev_b32_e32 v10, 16, v137
	v_and_b32_e32 v11, 0xffff0000, v137
	v_lshlrev_b32_e32 v12, 16, v138
	v_and_b32_e32 v13, 0xffff0000, v138
	v_lshlrev_b32_e32 v14, 16, v139
	v_and_b32_e32 v15, 0xffff0000, v139
	v_pk_add_f32 v[32:33], v[32:33], v[8:9]
	v_pk_add_f32 v[34:35], v[34:35], v[10:11]
	v_pk_add_f32 v[36:37], v[36:37], v[12:13]
	v_pk_add_f32 v[38:39], v[38:39], v[14:15]
	s_add_i32 s20, s14, 25
	s_add_i32 s15, s20, 1
	v_cmp_ge_u32_e32 vcc, s20, v52
	v_lshlrev_b32_e32 v16, 16, v140
	v_and_b32_e32 v17, 0xffff0000, v140
	v_lshlrev_b32_e32 v18, 16, v141
	v_and_b32_e32 v19, 0xffff0000, v141
	v_lshlrev_b32_e32 v20, 16, v142
	v_and_b32_e32 v21, 0xffff0000, v142
	v_lshlrev_b32_e32 v22, 16, v143
	v_and_b32_e32 v23, 0xffff0000, v143
	s_and_saveexec_b64 s[26:27], vcc
	v_pk_add_f32 v[32:33], v[32:33], v[16:17] neg_lo:[0,1] neg_hi:[0,1]
	v_pk_add_f32 v[34:35], v[34:35], v[18:19] neg_lo:[0,1] neg_hi:[0,1]
	v_pk_add_f32 v[36:37], v[36:37], v[20:21] neg_lo:[0,1] neg_hi:[0,1]
	v_pk_add_f32 v[38:39], v[38:39], v[22:23] neg_lo:[0,1] neg_hi:[0,1]
	s_or_b64 exec, exec, s[26:27]
	v_min_u32_e32 v40, s15, v52
	v_cvt_f32_ubyte0_e32 v40, v40
	v_div_scale_f32 v41, s[26:27], v40, v40, 1.0
	v_rcp_f32_e32 v42, v41
	v_div_scale_f32 v43, vcc, 1.0, v40, 1.0
	v_fma_f32 v44, -v41, v42, 1.0
	v_fmac_f32_e32 v42, v44, v42
	v_mul_f32_e32 v44, v43, v42
	v_fma_f32 v45, -v41, v44, v43
	v_fmac_f32_e32 v44, v45, v42
	v_fma_f32 v41, -v41, v44, v43
	v_div_fmas_f32 v41, v41, v42, v44
	v_div_fixup_f32 v40, v41, v40, 1.0
	v_fma_f32 v46, v40, v32, -v8
	v_fma_f32 v47, v40, v33, -v9
	v_cvt_pk_bf16_f32 v24, v46, v47
	v_fma_f32 v46, v40, v34, -v10
	v_fma_f32 v47, v40, v35, -v11
	v_cvt_pk_bf16_f32 v25, v46, v47
	v_fma_f32 v46, v40, v36, -v12
	v_fma_f32 v47, v40, v37, -v13
	v_cvt_pk_bf16_f32 v26, v46, v47
	v_fma_f32 v46, v40, v38, -v14
	v_fma_f32 v47, v40, v39, -v15
	v_cvt_pk_bf16_f32 v27, v46, v47
	global_store_dwordx4 v[28:29], v[24:27], off offset:2048
	s_nop 1
	s_waitcnt vmcnt(20)
; __device__ __forceinline__ float bf_lo(unsigned w) { return __uint_as_float(w << 16); }
; __device__ __forceinline__ float bf_hi(unsigned w) { return __uint_as_float(w & 0xffff0000u); }
; __device__ __forceinline__ unsigned pk2(float lo, float hi) { return pg8::cvt_pk_bf16(lo, hi); }
; __global__ void __launch_bounds__(NWAVES * 64, 2) trunk_fwd(Args args) {
;     ...
;                 for (int i0 = 0; i0 < 32; i0 += 4) {
;                     v4u qq[4], oo[4];
; #pragma unroll
;                     for (int k = 0; k < 4; ++k) { qq[k] = *(const v4u*)(up + (size_t)(i0 + k) * 2048); oo[k] = *(const v4u*)(up + ((long)(i0 + k) - w) * 2048); }
; #pragma unroll
;                     for (int k = 0; k < 4; ++k) { const int i = i0 + k; const v4u q = qq[k], o = oo[k];
;                     float cur[8] = {bf_lo(q.x), bf_hi(q.x), bf_lo(q.y), bf_hi(q.y), bf_lo(q.z), bf_hi(q.z), bf_lo(q.w), bf_hi(q.w)};
; #pragma unroll
;                     for (int e = 0; e < 8; ++e) sum[e] += cur[e];
;                     const int t = t0 + i;
;                     if (t - w >= 0) {
;                         sum[0] -= bf_lo(o.x); sum[1] -= bf_hi(o.x); sum[2] -= bf_lo(o.y); sum[3] -= bf_hi(o.y); sum[4] -= bf_lo(o.z); sum[5] -= bf_hi(o.z); sum[6] -= bf_lo(o.w); sum[7] -= bf_hi(o.w); }
;                     const float rc = 1.0f / (float)((t + 1) < w ? (t + 1) : w);
;                     v4u r; r.x = pk2(sum[0] * rc - cur[0], sum[1] * rc - cur[1]); r.y = pk2(sum[2] * rc - cur[2], sum[3] * rc - cur[3]); r.z = pk2(sum[4] * rc - cur[4], sum[5] * rc - cur[5]); r.w = pk2(sum[6] * rc - cur[6], sum[7] * rc - cur[7]);
;                     *(v4u*)(op + (size_t)i * 1024) = r; }
	v_lshlrev_b32_e32 v8, 16, v144
	v_and_b32_e32 v9, 0xffff0000, v144
	v_lshlrev_b32_e32 v10, 16, v145
	v_and_b32_e32 v11, 0xffff0000, v145
	v_lshlrev_b32_e32 v12, 16, v146
	v_and_b32_e32 v13, 0xffff0000, v146
	v_lshlrev_b32_e32 v14, 16, v147
	v_and_b32_e32 v15, 0xffff0000, v147
	v_pk_add_f32 v[32:33], v[32:33], v[8:9]
	v_pk_add_f32 v[34:35], v[34:35], v[10:11]
	v_pk_add_f32 v[36:37], v[36:37], v[12:13]
	v_pk_add_f32 v[38:39], v[38:39], v[14:15]
	s_add_i32 s20, s14, 26
	s_add_i32 s15, s20, 1
	v_cmp_ge_u32_e32 vcc, s20, v52
	v_lshlrev_b32_e32 v16, 16, v148
	v_and_b32_e32 v17, 0xffff0000, v148
	v_lshlrev_b32_e32 v18, 16, v149
	v_and_b32_e32 v19, 0xffff0000, v149
	v_lshlrev_b32_e32 v20, 16, v150
	v_and_b32_e32 v21, 0xffff0000, v150
	v_lshlrev_b32_e32 v22, 16, v151
	v_and_b32_e32 v23, 0xffff0000, v151
	s_and_saveexec_b64 s[26:27], vcc
	v_pk_add_f32 v[32:33], v[32:33], v[16:17] neg_lo:[0,1] neg_hi:[0,1]
	v_pk_add_f32 v[34:35], v[34:35], v[18:19] neg_lo:[0,1] neg_hi:[0,1]
	v_pk_add_f32 v[36:37], v[36:37], v[20:21] neg_lo:[0,1] neg_hi:[0,1]
	v_pk_add_f32 v[38:39], v[38:39], v[22:23] neg_lo:[0,1] neg_hi:[0,1]
	s_or_b64 exec, exec, s[26:27]
	v_min_u32_e32 v40, s15, v52
	v_cvt_f32_ubyte0_e32 v40, v40
	v_div_scale_f32 v41, s[26:27], v40, v40, 1.0
	v_rcp_f32_e32 v42, v41
	v_div_scale_f32 v43, vcc, 1.0, v40, 1.0
	v_fma_f32 v44, -v41, v42, 1.0
	v_fmac_f32_e32 v42, v44, v42
	v_mul_f32_e32 v44, v43, v42
	v_fma_f32 v45, -v41, v44, v43
	v_fmac_f32_e32 v44, v45, v42
	v_fma_f32 v41, -v41, v44, v43
	v_div_fmas_f32 v41, v41, v42, v44
	v_div_fixup_f32 v40, v41, v40, 1.0
	v_fma_f32 v46, v40, v32, -v8
	v_fma_f32 v47, v40, v33, -v9
	v_cvt_pk_bf16_f32 v24, v46, v47
	v_fma_f32 v46, v40, v34, -v10
	v_fma_f32 v47, v40, v35, -v11
	v_cvt_pk_bf16_f32 v25, v46, v47
	v_fma_f32 v46, v40, v36, -v12
	v_fma_f32 v47, v40, v37, -v13
	v_cvt_pk_bf16_f32 v26, v46, v47
	v_fma_f32 v46, v40, v38, -v14
	v_fma_f32 v47, v40, v39, -v15
	v_cvt_pk_bf16_f32 v27, v46, v47
	v_add_co_u32_e32 v28, vcc, 0xd000, v56
	s_nop 1
	v_addc_co_u32_e32 v29, vcc, 0, v57, vcc
	global_store_dwordx4 v[28:29], v[24:27], off
	s_waitcnt vmcnt(19)
	v_lshlrev_b32_e32 v8, 16, v152
	v_and_b32_e32 v9, 0xffff0000, v152
	v_lshlrev_b32_e32 v10, 16, v153
	v_and_b32_e32 v11, 0xffff0000, v153
	v_lshlrev_b32_e32 v12, 16, v154
	v_and_b32_e32 v13, 0xffff0000, v154
	v_lshlrev_b32_e32 v14, 16, v155
	v_and_b32_e32 v15, 0xffff0000, v155
	v_pk_add_f32 v[32:33], v[32:33], v[8:9]
	v_pk_add_f32 v[34:35], v[34:35], v[10:11]
	v_pk_add_f32 v[36:37], v[36:37], v[12:13]
	v_pk_add_f32 v[38:39], v[38:39], v[14:15]
	s_add_i32 s20, s14, 27
	s_add_i32 s15, s20, 1
	v_cmp_ge_u32_e32 vcc, s20, v52
	v_lshlrev_b32_e32 v16, 16, v156
	v_and_b32_e32 v17, 0xffff0000, v156
	v_lshlrev_b32_e32 v18, 16, v157
	v_and_b32_e32 v19, 0xffff0000, v157
	v_lshlrev_b32_e32 v20, 16, v158
	v_and_b32_e32 v21, 0xffff0000, v158
	v_lshlrev_b32_e32 v22, 16, v159
	v_and_b32_e32 v23, 0xffff0000, v159
	s_and_saveexec_b64 s[26:27], vcc
	v_pk_add_f32 v[32:33], v[32:33], v[16:17] neg_lo:[0,1] neg_hi:[0,1]
	v_pk_add_f32 v[34:35], v[34:35], v[18:19] neg_lo:[0,1] neg_hi:[0,1]
	v_pk_add_f32 v[36:37], v[36:37], v[20:21] neg_lo:[0,1] neg_hi:[0,1]
	v_pk_add_f32 v[38:39], v[38:39], v[22:23] neg_lo:[0,1] neg_hi:[0,1]
	s_or_b64 exec, exec, s[26:27]
	v_min_u32_e32 v40, s15, v52
	v_cvt_f32_ubyte0_e32 v40, v40
	v_div_scale_f32 v41, s[26:27], v40, v40, 1.0
	v_rcp_f32_e32 v42, v41
	v_div_scale_f32 v43, vcc, 1.0, v40, 1.0
	v_fma_f32 v44, -v41, v42, 1.0
	v_fmac_f32_e32 v42, v44, v42
	v_mul_f32_e32 v44, v43, v42
	v_fma_f32 v45, -v41, v44, v43
	v_fmac_f32_e32 v44, v45, v42
	v_fma_f32 v41, -v41, v44, v43
	v_div_fmas_f32 v41, v41, v42, v44
	v_div_fixup_f32 v40, v41, v40, 1.0
	v_fma_f32 v46, v40, v32, -v8
	v_fma_f32 v47, v40, v33, -v9
	v_cvt_pk_bf16_f32 v24, v46, v47
	v_fma_f32 v46, v40, v34, -v10
	v_fma_f32 v47, v40, v35, -v11
	v_cvt_pk_bf16_f32 v25, v46, v47
	v_fma_f32 v46, v40, v36, -v12
	v_fma_f32 v47, v40, v37, -v13
	v_cvt_pk_bf16_f32 v26, v46, v47
	v_fma_f32 v46, v40, v38, -v14
	v_fma_f32 v47, v40, v39, -v15
	v_cvt_pk_bf16_f32 v27, v46, v47
	global_store_dwordx4 v[28:29], v[24:27], off offset:2048
	s_nop 1
	s_waitcnt vmcnt(18)
	v_lshlrev_b32_e32 v8, 16, v160
	v_and_b32_e32 v9, 0xffff0000, v160
	v_lshlrev_b32_e32 v10, 16, v161
	v_and_b32_e32 v11, 0xffff0000, v161
	v_lshlrev_b32_e32 v12, 16, v162
	v_and_b32_e32 v13, 0xffff0000, v162
	v_lshlrev_b32_e32 v14, 16, v163
	v_and_b32_e32 v15, 0xffff0000, v163
	v_pk_add_f32 v[32:33], v[32:33], v[8:9]
	v_pk_add_f32 v[34:35], v[34:35], v[10:11]
	v_pk_add_f32 v[36:37], v[36:37], v[12:13]
	v_pk_add_f32 v[38:39], v[38:39], v[14:15]
	s_add_i32 s20, s14, 28
	s_add_i32 s15, s20, 1
	v_cmp_ge_u32_e32 vcc, s20, v52
	v_lshlrev_b32_e32 v16, 16, v164
	v_and_b32_e32 v17, 0xffff0000, v164
	v_lshlrev_b32_e32 v18, 16, v165
	v_and_b32_e32 v19, 0xffff0000, v165
	v_lshlrev_b32_e32 v20, 16, v166
	v_and_b32_e32 v21, 0xffff0000, v166
	v_lshlrev_b32_e32 v22, 16, v167
	v_and_b32_e32 v23, 0xffff0000, v167
	s_and_saveexec_b64 s[26:27], vcc
	v_pk_add_f32 v[32:33], v[32:33], v[16:17] neg_lo:[0,1] neg_hi:[0,1]
	v_pk_add_f32 v[34:35], v[34:35], v[18:19] neg_lo:[0,1] neg_hi:[0,1]
	v_pk_add_f32 v[36:37], v[36:37], v[20:21] neg_lo:[0,1] neg_hi:[0,1]
	v_pk_add_f32 v[38:39], v[38:39], v[22:23] neg_lo:[0,1] neg_hi:[0,1]
	s_or_b64 exec, exec, s[26:27]
	v_min_u32_e32 v40, s15, v52
	v_cvt_f32_ubyte0_e32 v40, v40
	v_div_scale_f32 v41, s[26:27], v40, v40, 1.0
	v_rcp_f32_e32 v42, v41
	v_div_scale_f32 v43, vcc, 1.0, v40, 1.0
	v_fma_f32 v44, -v41, v42, 1.0
	v_fmac_f32_e32 v42, v44, v42
	v_mul_f32_e32 v44, v43, v42
	v_fma_f32 v45, -v41, v44, v43
	v_fmac_f32_e32 v44, v45, v42
	v_fma_f32 v41, -v41, v44, v43
	v_div_fmas_f32 v41, v41, v42, v44
	v_div_fixup_f32 v40, v41, v40, 1.0
	v_fma_f32 v46, v40, v32, -v8
	v_fma_f32 v47, v40, v33, -v9
	v_cvt_pk_bf16_f32 v24, v46, v47
	v_fma_f32 v46, v40, v34, -v10
	v_fma_f32 v47, v40, v35, -v11
	v_cvt_pk_bf16_f32 v25, v46, v47
	v_fma_f32 v46, v40, v36, -v12
	v_fma_f32 v47, v40, v37, -v13
	v_cvt_pk_bf16_f32 v26, v46, v47
	v_fma_f32 v46, v40, v38, -v14
	v_fma_f32 v47, v40, v39, -v15
	v_cvt_pk_bf16_f32 v27, v46, v47
	v_add_co_u32_e32 v28, vcc, 0xe000, v56
	s_nop 1
	v_addc_co_u32_e32 v29, vcc, 0, v57, vcc
	global_store_dwordx4 v[28:29], v[24:27], off
	s_waitcnt vmcnt(17)
; __device__ __forceinline__ float bf_lo(unsigned w) { return __uint_as_float(w << 16); }
; __device__ __forceinline__ float bf_hi(unsigned w) { return __uint_as_float(w & 0xffff0000u); }
; __device__ __forceinline__ unsigned pk2(float lo, float hi) { return pg8::cvt_pk_bf16(lo, hi); }
; __global__ void __launch_bounds__(NWAVES * 64, 2) trunk_fwd(Args args) {
;     ...
;                 for (int i0 = 0; i0 < 32; i0 += 4) {
;                     v4u qq[4], oo[4];
; #pragma unroll
;                     for (int k = 0; k < 4; ++k) { qq[k] = *(const v4u*)(up + (size_t)(i0 + k) * 2048); oo[k] = *(const v4u*)(up + ((long)(i0 + k) - w) * 2048); }
; #pragma unroll
;                     for (int k = 0; k < 4; ++k) { const int i = i0 + k; const v4u q = qq[k], o = oo[k];
;                     float cur[8] = {bf_lo(q.x), bf_hi(q.x), bf_lo(q.y), bf_hi(q.y), bf_lo(q.z), bf_hi(q.z), bf_lo(q.w), bf_hi(q.w)};
; #pragma unroll
;                     for (int e = 0; e < 8; ++e) sum[e] += cur[e];
;                     const int t = t0 + i;
;                     if (t - w >= 0) {
;                         sum[0] -= bf_lo(o.x); sum[1] -= bf_hi(o.x); sum[2] -= bf_lo(o.y); sum[3] -= bf_hi(o.y); sum[4] -= bf_lo(o.z); sum[5] -= bf_hi(o.z); sum[6] -= bf_lo(o.w); sum[7] -= bf_hi(o.w); }
;                     const float rc = 1.0f / (float)((t + 1) < w ? (t + 1) : w);
;                     v4u r; r.x = pk2(sum[0] * rc - cur[0], sum[1] * rc - cur[1]); r.y = pk2(sum[2] * rc - cur[2], sum[3] * rc - cur[3]); r.z = pk2(sum[4] * rc - cur[4], sum[5] * rc - cur[5]); r.w = pk2(sum[6] * rc - cur[6], sum[7] * rc - cur[7]);
;                     *(v4u*)(op + (size_t)i * 1024) = r; }
	v_lshlrev_b32_e32 v8, 16, v168
	v_and_b32_e32 v9, 0xffff0000, v168
	v_lshlrev_b32_e32 v10, 16, v169
	v_and_b32_e32 v11, 0xffff0000, v169
	v_lshlrev_b32_e32 v12, 16, v170
	v_and_b32_e32 v13, 0xffff0000, v170
	v_lshlrev_b32_e32 v14, 16, v171
	v_and_b32_e32 v15, 0xffff0000, v171
	v_pk_add_f32 v[32:33], v[32:33], v[8:9]
	v_pk_add_f32 v[34:35], v[34:35], v[10:11]
	v_pk_add_f32 v[36:37], v[36:37], v[12:13]
	v_pk_add_f32 v[38:39], v[38:39], v[14:15]
	s_add_i32 s20, s14, 29
	s_add_i32 s15, s20, 1
	v_cmp_ge_u32_e32 vcc, s20, v52
	v_lshlrev_b32_e32 v16, 16, v172
	v_and_b32_e32 v17, 0xffff0000, v172
	v_lshlrev_b32_e32 v18, 16, v173
	v_and_b32_e32 v19, 0xffff0000, v173
	v_lshlrev_b32_e32 v20, 16, v174
	v_and_b32_e32 v21, 0xffff0000, v174
	v_lshlrev_b32_e32 v22, 16, v175
	v_and_b32_e32 v23, 0xffff0000, v175
	s_and_saveexec_b64 s[26:27], vcc
	v_pk_add_f32 v[32:33], v[32:33], v[16:17] neg_lo:[0,1] neg_hi:[0,1]
	v_pk_add_f32 v[34:35], v[34:35], v[18:19] neg_lo:[0,1] neg_hi:[0,1]
	v_pk_add_f32 v[36:37], v[36:37], v[20:21] neg_lo:[0,1] neg_hi:[0,1]
	v_pk_add_f32 v[38:39], v[38:39], v[22:23] neg_lo:[0,1] neg_hi:[0,1]
	s_or_b64 exec, exec, s[26:27]
	v_min_u32_e32 v40, s15, v52
	v_cvt_f32_ubyte0_e32 v40, v40
	v_div_scale_f32 v41, s[26:27], v40, v40, 1.0
	v_rcp_f32_e32 v42, v41
	v_div_scale_f32 v43, vcc, 1.0, v40, 1.0
	v_fma_f32 v44, -v41, v42, 1.0
	v_fmac_f32_e32 v42, v44, v42
	v_mul_f32_e32 v44, v43, v42
	v_fma_f32 v45, -v41, v44, v43
	v_fmac_f32_e32 v44, v45, v42
	v_fma_f32 v41, -v41, v44, v43
	v_div_fmas_f32 v41, v41, v42, v44
	v_div_fixup_f32 v40, v41, v40, 1.0
	v_fma_f32 v46, v40, v32, -v8
	v_fma_f32 v47, v40, v33, -v9
	v_cvt_pk_bf16_f32 v24, v46, v47
	v_fma_f32 v46, v40, v34, -v10
	v_fma_f32 v47, v40, v35, -v11
	v_cvt_pk_bf16_f32 v25, v46, v47
	v_fma_f32 v46, v40, v36, -v12
	v_fma_f32 v47, v40, v37, -v13
	v_cvt_pk_bf16_f32 v26, v46, v47
	v_fma_f32 v46, v40, v38, -v14
	v_fma_f32 v47, v40, v39, -v15
	v_cvt_pk_bf16_f32 v27, v46, v47
	global_store_dwordx4 v[28:29], v[24:27], off offset:2048
	s_nop 1
	s_waitcnt vmcnt(16)
	v_lshlrev_b32_e32 v8, 16, v176
	v_and_b32_e32 v9, 0xffff0000, v176
	v_lshlrev_b32_e32 v10, 16, v177
	v_and_b32_e32 v11, 0xffff0000, v177
	v_lshlrev_b32_e32 v12, 16, v178
	v_and_b32_e32 v13, 0xffff0000, v178
	v_lshlrev_b32_e32 v14, 16, v179
	v_and_b32_e32 v15, 0xffff0000, v179
	v_pk_add_f32 v[32:33], v[32:33], v[8:9]
	v_pk_add_f32 v[34:35], v[34:35], v[10:11]
	v_pk_add_f32 v[36:37], v[36:37], v[12:13]
	v_pk_add_f32 v[38:39], v[38:39], v[14:15]
	s_add_i32 s20, s14, 30
	s_add_i32 s15, s20, 1
	v_cmp_ge_u32_e32 vcc, s20, v52
	v_lshlrev_b32_e32 v16, 16, v180
	v_and_b32_e32 v17, 0xffff0000, v180
	v_lshlrev_b32_e32 v18, 16, v181
	v_and_b32_e32 v19, 0xffff0000, v181
	v_lshlrev_b32_e32 v20, 16, v182
	v_and_b32_e32 v21, 0xffff0000, v182
	v_lshlrev_b32_e32 v22, 16, v183
	v_and_b32_e32 v23, 0xffff0000, v183
	s_and_saveexec_b64 s[26:27], vcc
	v_pk_add_f32 v[32:33], v[32:33], v[16:17] neg_lo:[0,1] neg_hi:[0,1]
	v_pk_add_f32 v[34:35], v[34:35], v[18:19] neg_lo:[0,1] neg_hi:[0,1]
	v_pk_add_f32 v[36:37], v[36:37], v[20:21] neg_lo:[0,1] neg_hi:[0,1]
	v_pk_add_f32 v[38:39], v[38:39], v[22:23] neg_lo:[0,1] neg_hi:[0,1]
	s_or_b64 exec, exec, s[26:27]
	v_min_u32_e32 v40, s15, v52
	v_cvt_f32_ubyte0_e32 v40, v40
	v_div_scale_f32 v41, s[26:27], v40, v40, 1.0
	v_rcp_f32_e32 v42, v41
	v_div_scale_f32 v43, vcc, 1.0, v40, 1.0
	v_fma_f32 v44, -v41, v42, 1.0
	v_fmac_f32_e32 v42, v44, v42
	v_mul_f32_e32 v44, v43, v42
	v_fma_f32 v45, -v41, v44, v43
	v_fmac_f32_e32 v44, v45, v42
	v_fma_f32 v41, -v41, v44, v43
	v_div_fmas_f32 v41, v41, v42, v44
	v_div_fixup_f32 v40, v41, v40, 1.0
	v_fma_f32 v46, v40, v32, -v8
	v_fma_f32 v47, v40, v33, -v9
	v_cvt_pk_bf16_f32 v24, v46, v47
	v_fma_f32 v46, v40, v34, -v10
	v_fma_f32 v47, v40, v35, -v11
	v_cvt_pk_bf16_f32 v25, v46, v47
	v_fma_f32 v46, v40, v36, -v12
	v_fma_f32 v47, v40, v37, -v13
	v_cvt_pk_bf16_f32 v26, v46, v47
	v_fma_f32 v46, v40, v38, -v14
	v_fma_f32 v47, v40, v39, -v15
	v_cvt_pk_bf16_f32 v27, v46, v47
	v_add_co_u32_e32 v28, vcc, 0xf000, v56
	s_nop 1
	v_addc_co_u32_e32 v29, vcc, 0, v57, vcc
	global_store_dwordx4 v[28:29], v[24:27], off
	s_waitcnt vmcnt(15)
	v_lshlrev_b32_e32 v8, 16, v184
	v_and_b32_e32 v9, 0xffff0000, v184
	v_lshlrev_b32_e32 v10, 16, v185
	v_and_b32_e32 v11, 0xffff0000, v185
	v_lshlrev_b32_e32 v12, 16, v186
	v_and_b32_e32 v13, 0xffff0000, v186
	v_lshlrev_b32_e32 v14, 16, v187
	v_and_b32_e32 v15, 0xffff0000, v187
	v_pk_add_f32 v[32:33], v[32:33], v[8:9]
	v_pk_add_f32 v[34:35], v[34:35], v[10:11]
	v_pk_add_f32 v[36:37], v[36:37], v[12:13]
	v_pk_add_f32 v[38:39], v[38:39], v[14:15]
	s_add_i32 s20, s14, 31
	s_add_i32 s15, s20, 1
	v_cmp_ge_u32_e32 vcc, s20, v52
	v_lshlrev_b32_e32 v16, 16, v188
	v_and_b32_e32 v17, 0xffff0000, v188
	v_lshlrev_b32_e32 v18, 16, v189
	v_and_b32_e32 v19, 0xffff0000, v189
	v_lshlrev_b32_e32 v20, 16, v190
	v_and_b32_e32 v21, 0xffff0000, v190
	v_lshlrev_b32_e32 v22, 16, v191
	v_and_b32_e32 v23, 0xffff0000, v191
	s_and_saveexec_b64 s[26:27], vcc
	v_pk_add_f32 v[32:33], v[32:33], v[16:17] neg_lo:[0,1] neg_hi:[0,1]
	v_pk_add_f32 v[34:35], v[34:35], v[18:19] neg_lo:[0,1] neg_hi:[0,1]
	v_pk_add_f32 v[36:37], v[36:37], v[20:21] neg_lo:[0,1] neg_hi:[0,1]
	v_pk_add_f32 v[38:39], v[38:39], v[22:23] neg_lo:[0,1] neg_hi:[0,1]
	s_or_b64 exec, exec, s[26:27]
	v_min_u32_e32 v40, s15, v52
	v_cvt_f32_ubyte0_e32 v40, v40
	v_div_scale_f32 v41, s[26:27], v40, v40, 1.0
	v_rcp_f32_e32 v42, v41
	v_div_scale_f32 v43, vcc, 1.0, v40, 1.0
	v_fma_f32 v44, -v41, v42, 1.0
	v_fmac_f32_e32 v42, v44, v42
	v_mul_f32_e32 v44, v43, v42
	v_fma_f32 v45, -v41, v44, v43
	v_fmac_f32_e32 v44, v45, v42
	v_fma_f32 v41, -v41, v44, v43
	v_div_fmas_f32 v41, v41, v42, v44
	v_div_fixup_f32 v40, v41, v40, 1.0
	v_fma_f32 v46, v40, v32, -v8
	v_fma_f32 v47, v40, v33, -v9
	v_cvt_pk_bf16_f32 v24, v46, v47
	v_fma_f32 v46, v40, v34, -v10
	v_fma_f32 v47, v40, v35, -v11
	v_cvt_pk_bf16_f32 v25, v46, v47
	v_fma_f32 v46, v40, v36, -v12
	v_fma_f32 v47, v40, v37, -v13
	v_cvt_pk_bf16_f32 v26, v46, v47
	v_fma_f32 v46, v40, v38, -v14
	v_fma_f32 v47, v40, v39, -v15
	v_cvt_pk_bf16_f32 v27, v46, v47
	global_store_dwordx4 v[28:29], v[24:27], off offset:2048
	s_nop 1
	s_branch .LBB0_614
